# pipelined attention loop (half-tile software pipeline, 4 LDS tile buffers) + P1 GEMM mainloop with register-prefetched fragments
# speedup vs baseline: 1.0692x; 1.0692x over previous
.LBB0_164:
	s_mul_hi_i32 s18, s33, 0x2e8ba2e9
	s_lshr_b32 s19, s18, 31
	s_ashr_i32 s18, s18, 1
	s_add_i32 s24, s18, s19
	s_mul_i32 s18, s24, 11
	s_sub_i32 s18, s33, s18
	s_ashr_i32 s25, s24, 31
	s_ashr_i32 s19, s18, 31
	s_add_i32 s28, s18, -9
	s_lshl_b64 s[44:45], s[24:25], 19
	s_lshl_b64 s[46:47], s[18:19], 19
	s_add_u32 s19, s42, s44
	s_addc_u32 s25, s43, s45
	s_add_u32 s29, s48, s46
	s_addc_u32 s47, s49, s47
	s_cmp_lt_u32 s28, -4
	s_cselect_b32 s44, s29, s19
	s_cselect_b32 s46, s19, s29
	v_readfirstlane_b32 s19, v191
	s_cselect_b32 s45, s47, s25
	s_cselect_b32 s47, s25, s47
	s_lshr_b32 s53, s19, 6
	v_lshl_or_b32 v128, s53, 4, v193
	v_lshlrev_b32_e32 v128, 11, v128
	v_add_u32_e32 v128, v128, v140
	v_add_u32_e32 v129, 0x40000, v128
	s_lshl_b32 s54, s53, 10
	s_lshr_b32 s55, s19, 1
	s_and_b32 s55, s55, 0x3ffff80
	v_or_b32_e32 v130, s55, v189
	v_lshlrev_b32_e32 v149, 6, v130
	s_and_b32 s55, s19, 0xc0
	v_or_b32_e32 v131, s55, v189
	v_lshlrev_b32_e32 v150, 6, v131
	v_add_u32_e32 v130, v149, v152
	v_add_u32_e32 v131, v149, v201
	v_add_u32_e32 v132, v150, v152
	v_add_u32_e32 v141, v150, v201
	v_add_u32_e32 v145, 0x10000, v130
	v_add_u32_e32 v146, 0x10000, v131
	v_add_u32_e32 v147, 0x10000, v132
	v_add_u32_e32 v148, 0x10000, v141
	s_add_i32 m0, s54, 0x0
	s_nop 0
	global_load_lds_dwordx4 v128, s[44:45]
	s_add_i32 m0, s54, 0x4000
	s_nop 0
	global_load_lds_dwordx4 v128, s[46:47]
	s_add_i32 m0, s54, 0x2000
	s_nop 0
	global_load_lds_dwordx4 v129, s[44:45]
	s_add_i32 m0, s54, 0x6000
	s_nop 0
	global_load_lds_dwordx4 v129, s[46:47]
	s_add_u32 s44, s44, 64
	s_addc_u32 s45, s45, 0
	s_add_u32 s46, s46, 64
	s_addc_u32 s47, s47, 0
	s_add_i32 m0, s54, 0x8000
	s_nop 0
	global_load_lds_dwordx4 v128, s[44:45]
	s_add_i32 m0, s54, 0xc000
	s_nop 0
	global_load_lds_dwordx4 v128, s[46:47]
	s_add_i32 m0, s54, 0xa000
	s_nop 0
	global_load_lds_dwordx4 v129, s[44:45]
	s_add_i32 m0, s54, 0xe000
	s_nop 0
	global_load_lds_dwordx4 v129, s[46:47]
	s_add_u32 s44, s44, 64
	s_addc_u32 s45, s45, 0
	s_add_u32 s46, s46, 64
	s_addc_u32 s47, s47, 0
	s_add_i32 m0, s54, 0x10000
	s_nop 0
	global_load_lds_dwordx4 v128, s[44:45]
	s_add_i32 m0, s54, 0x14000
	s_nop 0
	global_load_lds_dwordx4 v128, s[46:47]
	s_add_i32 m0, s54, 0x12000
	s_nop 0
	global_load_lds_dwordx4 v129, s[44:45]
	s_add_i32 m0, s54, 0x16000
	s_nop 0
	global_load_lds_dwordx4 v129, s[46:47]
	s_add_u32 s44, s44, 64
	s_addc_u32 s45, s45, 0
	s_add_u32 s46, s46, 64
	s_addc_u32 s47, s47, 0
	v_mov_b32_e32 v112, 0
	v_mov_b32_e32 v113, 0
	v_mov_b32_e32 v114, 0
	v_mov_b32_e32 v115, 0
	v_mov_b32_e32 v116, 0
	v_mov_b32_e32 v117, 0
	v_mov_b32_e32 v118, 0
	v_mov_b32_e32 v119, 0
	v_mov_b32_e32 v120, 0
	v_mov_b32_e32 v121, 0
	v_mov_b32_e32 v122, 0
	v_mov_b32_e32 v123, 0
	v_mov_b32_e32 v124, 0
	v_mov_b32_e32 v125, 0
	v_mov_b32_e32 v126, 0
	v_mov_b32_e32 v127, 0
	v_mov_b32_e32 v48, 0
	v_mov_b32_e32 v49, 0
	v_mov_b32_e32 v50, 0
	v_mov_b32_e32 v51, 0
	v_mov_b32_e32 v52, 0
	v_mov_b32_e32 v53, 0
	v_mov_b32_e32 v54, 0
	v_mov_b32_e32 v55, 0
	v_mov_b32_e32 v56, 0
	v_mov_b32_e32 v57, 0
	v_mov_b32_e32 v58, 0
	v_mov_b32_e32 v59, 0
	v_mov_b32_e32 v60, 0
	v_mov_b32_e32 v61, 0
	v_mov_b32_e32 v62, 0
	v_mov_b32_e32 v63, 0
	v_mov_b32_e32 v96, 0
	v_mov_b32_e32 v97, 0
	v_mov_b32_e32 v98, 0
	v_mov_b32_e32 v99, 0
	v_mov_b32_e32 v100, 0
	v_mov_b32_e32 v101, 0
	v_mov_b32_e32 v102, 0
	v_mov_b32_e32 v103, 0
	v_mov_b32_e32 v104, 0
	v_mov_b32_e32 v105, 0
	v_mov_b32_e32 v106, 0
	v_mov_b32_e32 v107, 0
	v_mov_b32_e32 v108, 0
	v_mov_b32_e32 v109, 0
	v_mov_b32_e32 v110, 0
	v_mov_b32_e32 v111, 0
	v_mov_b32_e32 v32, 0
	v_mov_b32_e32 v33, 0
	v_mov_b32_e32 v34, 0
	v_mov_b32_e32 v35, 0
	v_mov_b32_e32 v36, 0
	v_mov_b32_e32 v37, 0
	v_mov_b32_e32 v38, 0
	v_mov_b32_e32 v39, 0
	v_mov_b32_e32 v40, 0
	v_mov_b32_e32 v41, 0
	v_mov_b32_e32 v42, 0
	v_mov_b32_e32 v43, 0
	v_mov_b32_e32 v44, 0
	v_mov_b32_e32 v45, 0
	v_mov_b32_e32 v46, 0
	v_mov_b32_e32 v47, 0
	v_mov_b32_e32 v80, 0
	v_mov_b32_e32 v81, 0
	v_mov_b32_e32 v82, 0
	v_mov_b32_e32 v83, 0
	v_mov_b32_e32 v84, 0
	v_mov_b32_e32 v85, 0
	v_mov_b32_e32 v86, 0
	v_mov_b32_e32 v87, 0
	v_mov_b32_e32 v88, 0
	v_mov_b32_e32 v89, 0
	v_mov_b32_e32 v90, 0
	v_mov_b32_e32 v91, 0
	v_mov_b32_e32 v92, 0
	v_mov_b32_e32 v93, 0
	v_mov_b32_e32 v94, 0
	v_mov_b32_e32 v95, 0
	v_mov_b32_e32 v0, 0
	v_mov_b32_e32 v1, 0
	v_mov_b32_e32 v2, 0
	v_mov_b32_e32 v3, 0
	v_mov_b32_e32 v4, 0
	v_mov_b32_e32 v5, 0
	v_mov_b32_e32 v6, 0
	v_mov_b32_e32 v7, 0
	v_mov_b32_e32 v8, 0
	v_mov_b32_e32 v9, 0
	v_mov_b32_e32 v10, 0
	v_mov_b32_e32 v11, 0
	v_mov_b32_e32 v12, 0
	v_mov_b32_e32 v13, 0
	v_mov_b32_e32 v14, 0
	v_mov_b32_e32 v15, 0
	v_mov_b32_e32 v64, 0
	v_mov_b32_e32 v65, 0
	v_mov_b32_e32 v66, 0
	v_mov_b32_e32 v67, 0
	v_mov_b32_e32 v68, 0
	v_mov_b32_e32 v69, 0
	v_mov_b32_e32 v70, 0
	v_mov_b32_e32 v71, 0
	v_mov_b32_e32 v72, 0
	v_mov_b32_e32 v73, 0
	v_mov_b32_e32 v74, 0
	v_mov_b32_e32 v75, 0
	v_mov_b32_e32 v76, 0
	v_mov_b32_e32 v77, 0
	v_mov_b32_e32 v78, 0
	v_mov_b32_e32 v79, 0
	v_mov_b32_e32 v16, 0
	v_mov_b32_e32 v17, 0
	v_mov_b32_e32 v18, 0
	v_mov_b32_e32 v19, 0
	v_mov_b32_e32 v20, 0
	v_mov_b32_e32 v21, 0
	v_mov_b32_e32 v22, 0
	v_mov_b32_e32 v23, 0
	v_mov_b32_e32 v24, 0
	v_mov_b32_e32 v25, 0
	v_mov_b32_e32 v26, 0
	v_mov_b32_e32 v27, 0
	v_mov_b32_e32 v28, 0
	v_mov_b32_e32 v29, 0
	v_mov_b32_e32 v30, 0
	v_mov_b32_e32 v31, 0
	s_waitcnt vmcnt(8)
	s_barrier
	ds_read_b128 v[238:241], v132 offset:16384
	ds_read_b128 v[222:225], v130
	ds_read_b128 v[242:245], v132 offset:18432
	ds_read_b128 v[226:229], v130 offset:2048
	ds_read_b128 v[230:233], v130 offset:4096
	s_mov_b32 s50, 8
.Lg1_loop:
	s_waitcnt vmcnt(4)
	s_barrier
	s_add_i32 m0, s54, 0x18000
	s_waitcnt lgkmcnt(3)
	v_mfma_f32_32x32x16_bf16 v[112:127], v[222:225], v[238:241], v[112:127]
	global_load_lds_dwordx4 v128, s[44:45]
	s_waitcnt lgkmcnt(2)
	v_mfma_f32_32x32x16_bf16 v[48:63], v[222:225], v[242:245], v[48:63]
	ds_read_b128 v[234:237], v130 offset:6144
	ds_read_b128 v[246:249], v141 offset:16384
	s_add_i32 m0, s54, 0x1c000
	s_waitcnt lgkmcnt(3)
	v_mfma_f32_32x32x16_bf16 v[96:111], v[226:229], v[238:241], v[96:111]
	global_load_lds_dwordx4 v128, s[46:47]
	v_mfma_f32_32x32x16_bf16 v[32:47], v[226:229], v[242:245], v[32:47]
	ds_read_b128 v[222:225], v131
	ds_read_b128 v[250:253], v141 offset:18432
	s_add_i32 m0, s54, 0x1a000
	s_waitcnt lgkmcnt(4)
	v_mfma_f32_32x32x16_bf16 v[80:95], v[230:233], v[238:241], v[80:95]
	global_load_lds_dwordx4 v129, s[44:45]
	v_mfma_f32_32x32x16_bf16 v[0:15], v[230:233], v[242:245], v[0:15]
	ds_read_b128 v[226:229], v131 offset:2048
	s_add_i32 m0, s54, 0x1e000
	s_waitcnt lgkmcnt(4)
	v_mfma_f32_32x32x16_bf16 v[64:79], v[234:237], v[238:241], v[64:79]
	global_load_lds_dwordx4 v129, s[46:47]
	v_mfma_f32_32x32x16_bf16 v[16:31], v[234:237], v[242:245], v[16:31]
	s_add_u32 s44, s44, 64
	s_addc_u32 s45, s45, 0
	s_add_u32 s46, s46, 64
	s_addc_u32 s47, s47, 0
	ds_read_b128 v[230:233], v131 offset:4096
	s_waitcnt lgkmcnt(3)
	v_mfma_f32_32x32x16_bf16 v[112:127], v[222:225], v[246:249], v[112:127]
	s_waitcnt lgkmcnt(2)
	v_mfma_f32_32x32x16_bf16 v[48:63], v[222:225], v[250:253], v[48:63]
	ds_read_b128 v[234:237], v131 offset:6144
	ds_read_b128 v[238:241], v132 offset:49152
	s_waitcnt lgkmcnt(3)
	v_mfma_f32_32x32x16_bf16 v[96:111], v[226:229], v[246:249], v[96:111]
	v_mfma_f32_32x32x16_bf16 v[32:47], v[226:229], v[250:253], v[32:47]
	ds_read_b128 v[222:225], v130 offset:32768
	ds_read_b128 v[242:245], v132 offset:51200
	s_waitcnt lgkmcnt(4)
	v_mfma_f32_32x32x16_bf16 v[80:95], v[230:233], v[246:249], v[80:95]
	v_mfma_f32_32x32x16_bf16 v[0:15], v[230:233], v[250:253], v[0:15]
	ds_read_b128 v[226:229], v130 offset:34816
	s_waitcnt lgkmcnt(4)
	v_mfma_f32_32x32x16_bf16 v[64:79], v[234:237], v[246:249], v[64:79]
	v_mfma_f32_32x32x16_bf16 v[16:31], v[234:237], v[250:253], v[16:31]
	ds_read_b128 v[230:233], v130 offset:36864
	s_add_i32 s50, s50, -1
	s_cmp_eq_u32 s50, 0
	s_cbranch_scc1 .Lg1_tail
	s_waitcnt vmcnt(4)
	s_barrier
	s_add_i32 m0, s54, 0x0
	s_waitcnt lgkmcnt(3)
	v_mfma_f32_32x32x16_bf16 v[112:127], v[222:225], v[238:241], v[112:127]
	global_load_lds_dwordx4 v128, s[44:45]
	s_waitcnt lgkmcnt(2)
	v_mfma_f32_32x32x16_bf16 v[48:63], v[222:225], v[242:245], v[48:63]
	ds_read_b128 v[234:237], v130 offset:38912
	ds_read_b128 v[246:249], v141 offset:49152
	s_add_i32 m0, s54, 0x4000
	s_waitcnt lgkmcnt(3)
	v_mfma_f32_32x32x16_bf16 v[96:111], v[226:229], v[238:241], v[96:111]
	global_load_lds_dwordx4 v128, s[46:47]
	v_mfma_f32_32x32x16_bf16 v[32:47], v[226:229], v[242:245], v[32:47]
	ds_read_b128 v[222:225], v131 offset:32768
	ds_read_b128 v[250:253], v141 offset:51200
	s_add_i32 m0, s54, 0x2000
	s_waitcnt lgkmcnt(4)
	v_mfma_f32_32x32x16_bf16 v[80:95], v[230:233], v[238:241], v[80:95]
	global_load_lds_dwordx4 v129, s[44:45]
	v_mfma_f32_32x32x16_bf16 v[0:15], v[230:233], v[242:245], v[0:15]
	ds_read_b128 v[226:229], v131 offset:34816
	s_add_i32 m0, s54, 0x6000
	s_waitcnt lgkmcnt(4)
	v_mfma_f32_32x32x16_bf16 v[64:79], v[234:237], v[238:241], v[64:79]
	global_load_lds_dwordx4 v129, s[46:47]
	v_mfma_f32_32x32x16_bf16 v[16:31], v[234:237], v[242:245], v[16:31]
	s_add_u32 s44, s44, 64
	s_addc_u32 s45, s45, 0
	s_add_u32 s46, s46, 64
	s_addc_u32 s47, s47, 0
	ds_read_b128 v[230:233], v131 offset:36864
	s_waitcnt lgkmcnt(3)
	v_mfma_f32_32x32x16_bf16 v[112:127], v[222:225], v[246:249], v[112:127]
	s_waitcnt lgkmcnt(2)
	v_mfma_f32_32x32x16_bf16 v[48:63], v[222:225], v[250:253], v[48:63]
	ds_read_b128 v[234:237], v131 offset:38912
	ds_read_b128 v[238:241], v147 offset:16384
	s_waitcnt lgkmcnt(3)
	v_mfma_f32_32x32x16_bf16 v[96:111], v[226:229], v[246:249], v[96:111]
	v_mfma_f32_32x32x16_bf16 v[32:47], v[226:229], v[250:253], v[32:47]
	ds_read_b128 v[222:225], v145
	ds_read_b128 v[242:245], v147 offset:18432
	s_waitcnt lgkmcnt(4)
	v_mfma_f32_32x32x16_bf16 v[80:95], v[230:233], v[246:249], v[80:95]
	v_mfma_f32_32x32x16_bf16 v[0:15], v[230:233], v[250:253], v[0:15]
	ds_read_b128 v[226:229], v145 offset:2048
	s_waitcnt lgkmcnt(4)
	v_mfma_f32_32x32x16_bf16 v[64:79], v[234:237], v[246:249], v[64:79]
	v_mfma_f32_32x32x16_bf16 v[16:31], v[234:237], v[250:253], v[16:31]
	ds_read_b128 v[230:233], v145 offset:4096
	s_waitcnt vmcnt(4)
	s_barrier
	s_add_i32 m0, s54, 0x8000
	s_waitcnt lgkmcnt(3)
	v_mfma_f32_32x32x16_bf16 v[112:127], v[222:225], v[238:241], v[112:127]
	global_load_lds_dwordx4 v128, s[44:45]
	s_waitcnt lgkmcnt(2)
	v_mfma_f32_32x32x16_bf16 v[48:63], v[222:225], v[242:245], v[48:63]
	ds_read_b128 v[234:237], v145 offset:6144
	ds_read_b128 v[246:249], v148 offset:16384
	s_add_i32 m0, s54, 0xc000
	s_waitcnt lgkmcnt(3)
	v_mfma_f32_32x32x16_bf16 v[96:111], v[226:229], v[238:241], v[96:111]
	global_load_lds_dwordx4 v128, s[46:47]
	v_mfma_f32_32x32x16_bf16 v[32:47], v[226:229], v[242:245], v[32:47]
	ds_read_b128 v[222:225], v146
	ds_read_b128 v[250:253], v148 offset:18432
	s_add_i32 m0, s54, 0xa000
	s_waitcnt lgkmcnt(4)
	v_mfma_f32_32x32x16_bf16 v[80:95], v[230:233], v[238:241], v[80:95]
	global_load_lds_dwordx4 v129, s[44:45]
	v_mfma_f32_32x32x16_bf16 v[0:15], v[230:233], v[242:245], v[0:15]
	ds_read_b128 v[226:229], v146 offset:2048
	s_add_i32 m0, s54, 0xe000
	s_waitcnt lgkmcnt(4)
	v_mfma_f32_32x32x16_bf16 v[64:79], v[234:237], v[238:241], v[64:79]
	global_load_lds_dwordx4 v129, s[46:47]
	v_mfma_f32_32x32x16_bf16 v[16:31], v[234:237], v[242:245], v[16:31]
	s_add_u32 s44, s44, 64
	s_addc_u32 s45, s45, 0
	s_add_u32 s46, s46, 64
	s_addc_u32 s47, s47, 0
	ds_read_b128 v[230:233], v146 offset:4096
	s_waitcnt lgkmcnt(3)
	v_mfma_f32_32x32x16_bf16 v[112:127], v[222:225], v[246:249], v[112:127]
	s_waitcnt lgkmcnt(2)
	v_mfma_f32_32x32x16_bf16 v[48:63], v[222:225], v[250:253], v[48:63]
	ds_read_b128 v[234:237], v146 offset:6144
	ds_read_b128 v[238:241], v147 offset:49152
	s_waitcnt lgkmcnt(3)
	v_mfma_f32_32x32x16_bf16 v[96:111], v[226:229], v[246:249], v[96:111]
	v_mfma_f32_32x32x16_bf16 v[32:47], v[226:229], v[250:253], v[32:47]
	ds_read_b128 v[222:225], v145 offset:32768
	ds_read_b128 v[242:245], v147 offset:51200
	s_waitcnt lgkmcnt(4)
	v_mfma_f32_32x32x16_bf16 v[80:95], v[230:233], v[246:249], v[80:95]
	v_mfma_f32_32x32x16_bf16 v[0:15], v[230:233], v[250:253], v[0:15]
	ds_read_b128 v[226:229], v145 offset:34816
	s_waitcnt lgkmcnt(4)
	v_mfma_f32_32x32x16_bf16 v[64:79], v[234:237], v[246:249], v[64:79]
	v_mfma_f32_32x32x16_bf16 v[16:31], v[234:237], v[250:253], v[16:31]
	ds_read_b128 v[230:233], v145 offset:36864
	s_waitcnt vmcnt(4)
	s_barrier
	s_add_i32 m0, s54, 0x10000
	s_waitcnt lgkmcnt(3)
	v_mfma_f32_32x32x16_bf16 v[112:127], v[222:225], v[238:241], v[112:127]
	global_load_lds_dwordx4 v128, s[44:45]
	s_waitcnt lgkmcnt(2)
	v_mfma_f32_32x32x16_bf16 v[48:63], v[222:225], v[242:245], v[48:63]
	ds_read_b128 v[234:237], v145 offset:38912
	ds_read_b128 v[246:249], v148 offset:49152
	s_add_i32 m0, s54, 0x14000
	s_waitcnt lgkmcnt(3)
	v_mfma_f32_32x32x16_bf16 v[96:111], v[226:229], v[238:241], v[96:111]
	global_load_lds_dwordx4 v128, s[46:47]
	v_mfma_f32_32x32x16_bf16 v[32:47], v[226:229], v[242:245], v[32:47]
	ds_read_b128 v[222:225], v146 offset:32768
	ds_read_b128 v[250:253], v148 offset:51200
	s_add_i32 m0, s54, 0x12000
	s_waitcnt lgkmcnt(4)
	v_mfma_f32_32x32x16_bf16 v[80:95], v[230:233], v[238:241], v[80:95]
	global_load_lds_dwordx4 v129, s[44:45]
	v_mfma_f32_32x32x16_bf16 v[0:15], v[230:233], v[242:245], v[0:15]
	ds_read_b128 v[226:229], v146 offset:34816
	s_add_i32 m0, s54, 0x16000
	s_waitcnt lgkmcnt(4)
	v_mfma_f32_32x32x16_bf16 v[64:79], v[234:237], v[238:241], v[64:79]
	global_load_lds_dwordx4 v129, s[46:47]
	v_mfma_f32_32x32x16_bf16 v[16:31], v[234:237], v[242:245], v[16:31]
	s_add_u32 s44, s44, 64
	s_addc_u32 s45, s45, 0
	s_add_u32 s46, s46, 64
	s_addc_u32 s47, s47, 0
	ds_read_b128 v[230:233], v146 offset:36864
	s_waitcnt lgkmcnt(3)
	v_mfma_f32_32x32x16_bf16 v[112:127], v[222:225], v[246:249], v[112:127]
	s_waitcnt lgkmcnt(2)
	v_mfma_f32_32x32x16_bf16 v[48:63], v[222:225], v[250:253], v[48:63]
	ds_read_b128 v[234:237], v146 offset:38912
	ds_read_b128 v[238:241], v132 offset:16384
	s_waitcnt lgkmcnt(3)
	v_mfma_f32_32x32x16_bf16 v[96:111], v[226:229], v[246:249], v[96:111]
	v_mfma_f32_32x32x16_bf16 v[32:47], v[226:229], v[250:253], v[32:47]
	ds_read_b128 v[222:225], v130
	ds_read_b128 v[242:245], v132 offset:18432
	s_waitcnt lgkmcnt(4)
	v_mfma_f32_32x32x16_bf16 v[80:95], v[230:233], v[246:249], v[80:95]
	v_mfma_f32_32x32x16_bf16 v[0:15], v[230:233], v[250:253], v[0:15]
	ds_read_b128 v[226:229], v130 offset:2048
	s_waitcnt lgkmcnt(4)
	v_mfma_f32_32x32x16_bf16 v[64:79], v[234:237], v[246:249], v[64:79]
	v_mfma_f32_32x32x16_bf16 v[16:31], v[234:237], v[250:253], v[16:31]
	ds_read_b128 v[230:233], v130 offset:4096
	s_branch .Lg1_loop
.Lg1_tail:
	s_waitcnt vmcnt(4)
	s_barrier
	s_waitcnt lgkmcnt(3)
	v_mfma_f32_32x32x16_bf16 v[112:127], v[222:225], v[238:241], v[112:127]
	s_waitcnt lgkmcnt(2)
	v_mfma_f32_32x32x16_bf16 v[48:63], v[222:225], v[242:245], v[48:63]
	ds_read_b128 v[234:237], v130 offset:38912
	ds_read_b128 v[246:249], v141 offset:49152
	s_waitcnt lgkmcnt(3)
	v_mfma_f32_32x32x16_bf16 v[96:111], v[226:229], v[238:241], v[96:111]
	v_mfma_f32_32x32x16_bf16 v[32:47], v[226:229], v[242:245], v[32:47]
	ds_read_b128 v[222:225], v131 offset:32768
	ds_read_b128 v[250:253], v141 offset:51200
	s_waitcnt lgkmcnt(4)
	v_mfma_f32_32x32x16_bf16 v[80:95], v[230:233], v[238:241], v[80:95]
	v_mfma_f32_32x32x16_bf16 v[0:15], v[230:233], v[242:245], v[0:15]
	ds_read_b128 v[226:229], v131 offset:34816
	s_waitcnt lgkmcnt(4)
	v_mfma_f32_32x32x16_bf16 v[64:79], v[234:237], v[238:241], v[64:79]
	v_mfma_f32_32x32x16_bf16 v[16:31], v[234:237], v[242:245], v[16:31]
	ds_read_b128 v[230:233], v131 offset:36864
	s_waitcnt lgkmcnt(3)
	v_mfma_f32_32x32x16_bf16 v[112:127], v[222:225], v[246:249], v[112:127]
	s_waitcnt lgkmcnt(2)
	v_mfma_f32_32x32x16_bf16 v[48:63], v[222:225], v[250:253], v[48:63]
	ds_read_b128 v[234:237], v131 offset:38912
	ds_read_b128 v[238:241], v147 offset:16384
	s_waitcnt lgkmcnt(3)
	v_mfma_f32_32x32x16_bf16 v[96:111], v[226:229], v[246:249], v[96:111]
	v_mfma_f32_32x32x16_bf16 v[32:47], v[226:229], v[250:253], v[32:47]
	ds_read_b128 v[222:225], v145
	ds_read_b128 v[242:245], v147 offset:18432
	s_waitcnt lgkmcnt(4)
	v_mfma_f32_32x32x16_bf16 v[80:95], v[230:233], v[246:249], v[80:95]
	v_mfma_f32_32x32x16_bf16 v[0:15], v[230:233], v[250:253], v[0:15]
	ds_read_b128 v[226:229], v145 offset:2048
	s_waitcnt lgkmcnt(4)
	v_mfma_f32_32x32x16_bf16 v[64:79], v[234:237], v[246:249], v[64:79]
	v_mfma_f32_32x32x16_bf16 v[16:31], v[234:237], v[250:253], v[16:31]
	ds_read_b128 v[230:233], v145 offset:4096
	s_waitcnt vmcnt(0)
	s_barrier
	s_waitcnt lgkmcnt(3)
	v_mfma_f32_32x32x16_bf16 v[112:127], v[222:225], v[238:241], v[112:127]
	s_waitcnt lgkmcnt(2)
	v_mfma_f32_32x32x16_bf16 v[48:63], v[222:225], v[242:245], v[48:63]
	ds_read_b128 v[234:237], v145 offset:6144
	ds_read_b128 v[246:249], v148 offset:16384
	s_waitcnt lgkmcnt(3)
	v_mfma_f32_32x32x16_bf16 v[96:111], v[226:229], v[238:241], v[96:111]
	v_mfma_f32_32x32x16_bf16 v[32:47], v[226:229], v[242:245], v[32:47]
	ds_read_b128 v[222:225], v146
	ds_read_b128 v[250:253], v148 offset:18432
	s_waitcnt lgkmcnt(4)
	v_mfma_f32_32x32x16_bf16 v[80:95], v[230:233], v[238:241], v[80:95]
	v_mfma_f32_32x32x16_bf16 v[0:15], v[230:233], v[242:245], v[0:15]
	ds_read_b128 v[226:229], v146 offset:2048
	s_waitcnt lgkmcnt(4)
	v_mfma_f32_32x32x16_bf16 v[64:79], v[234:237], v[238:241], v[64:79]
	v_mfma_f32_32x32x16_bf16 v[16:31], v[234:237], v[242:245], v[16:31]
	ds_read_b128 v[230:233], v146 offset:4096
	s_waitcnt lgkmcnt(3)
	v_mfma_f32_32x32x16_bf16 v[112:127], v[222:225], v[246:249], v[112:127]
	s_waitcnt lgkmcnt(2)
	v_mfma_f32_32x32x16_bf16 v[48:63], v[222:225], v[250:253], v[48:63]
	ds_read_b128 v[234:237], v146 offset:6144
	ds_read_b128 v[238:241], v147 offset:49152
	s_waitcnt lgkmcnt(3)
	v_mfma_f32_32x32x16_bf16 v[96:111], v[226:229], v[246:249], v[96:111]
	v_mfma_f32_32x32x16_bf16 v[32:47], v[226:229], v[250:253], v[32:47]
	ds_read_b128 v[222:225], v145 offset:32768
	ds_read_b128 v[242:245], v147 offset:51200
	s_waitcnt lgkmcnt(4)
	v_mfma_f32_32x32x16_bf16 v[80:95], v[230:233], v[246:249], v[80:95]
	v_mfma_f32_32x32x16_bf16 v[0:15], v[230:233], v[250:253], v[0:15]
	ds_read_b128 v[226:229], v145 offset:34816
	s_waitcnt lgkmcnt(4)
	v_mfma_f32_32x32x16_bf16 v[64:79], v[234:237], v[246:249], v[64:79]
	v_mfma_f32_32x32x16_bf16 v[16:31], v[234:237], v[250:253], v[16:31]
	ds_read_b128 v[230:233], v145 offset:36864
	s_waitcnt lgkmcnt(3)
	v_mfma_f32_32x32x16_bf16 v[112:127], v[222:225], v[238:241], v[112:127]
	s_waitcnt lgkmcnt(2)
	v_mfma_f32_32x32x16_bf16 v[48:63], v[222:225], v[242:245], v[48:63]
	ds_read_b128 v[234:237], v145 offset:38912
	ds_read_b128 v[246:249], v148 offset:49152
	s_waitcnt lgkmcnt(3)
	v_mfma_f32_32x32x16_bf16 v[96:111], v[226:229], v[238:241], v[96:111]
	v_mfma_f32_32x32x16_bf16 v[32:47], v[226:229], v[242:245], v[32:47]
	ds_read_b128 v[222:225], v146 offset:32768
	ds_read_b128 v[250:253], v148 offset:51200
	s_waitcnt lgkmcnt(4)
	v_mfma_f32_32x32x16_bf16 v[80:95], v[230:233], v[238:241], v[80:95]
	v_mfma_f32_32x32x16_bf16 v[0:15], v[230:233], v[242:245], v[0:15]
	ds_read_b128 v[226:229], v146 offset:34816
	s_waitcnt lgkmcnt(4)
	v_mfma_f32_32x32x16_bf16 v[64:79], v[234:237], v[238:241], v[64:79]
	v_mfma_f32_32x32x16_bf16 v[16:31], v[234:237], v[242:245], v[16:31]
	ds_read_b128 v[230:233], v146 offset:36864
	s_waitcnt lgkmcnt(3)
	v_mfma_f32_32x32x16_bf16 v[112:127], v[222:225], v[246:249], v[112:127]
	s_waitcnt lgkmcnt(2)
	v_mfma_f32_32x32x16_bf16 v[48:63], v[222:225], v[250:253], v[48:63]
	ds_read_b128 v[234:237], v146 offset:38912
	s_waitcnt lgkmcnt(2)
	v_mfma_f32_32x32x16_bf16 v[96:111], v[226:229], v[246:249], v[96:111]
	v_mfma_f32_32x32x16_bf16 v[32:47], v[226:229], v[250:253], v[32:47]
	s_waitcnt lgkmcnt(1)
	v_mfma_f32_32x32x16_bf16 v[80:95], v[230:233], v[246:249], v[80:95]
	v_mfma_f32_32x32x16_bf16 v[0:15], v[230:233], v[250:253], v[0:15]
	s_waitcnt lgkmcnt(0)
	v_mfma_f32_32x32x16_bf16 v[64:79], v[234:237], v[246:249], v[64:79]
	v_mfma_f32_32x32x16_bf16 v[16:31], v[234:237], v[250:253], v[16:31]
	s_barrier
	s_lshl_b32 s52, s24, 8
	s_cmpk_lt_i32 s33, 0x580
	s_cselect_b64 s[58:59], -1, 0
	s_movk_i32 s19, 0xf000
	s_and_b64 s[24:25], s[58:59], exec
	s_cselect_b32 s19, s19, 0x7fffe000
	s_and_b32 s24, s19, s52
	s_cmp_gt_u32 s28, -5
	s_mov_b64 s[28:29], -1
	s_cbranch_scc0 .LBB0_168
	v_add_u32_e32 v128, s52, v202
	v_ashrrev_i32_e32 v129, 31, v128
	v_lshl_add_u64 v[128:129], v[128:129], 2, s[6:7]
	global_load_dwordx4 v[146:149], v[128:129], off
	v_add_u32_e32 v132, v204, v154
	s_ashr_i32 s25, s24, 31
	s_add_i32 s50, s18, -5
	s_lshl_b64 s[28:29], s[24:25], 11
	s_lshl_b64 s[44:45], s[50:51], 8
	s_and_b64 s[46:47], s[58:59], exec
	s_cselect_b32 s19, 12, 13
	s_lshl_b64 s[44:45], s[44:45], s19
	s_add_u32 s46, s40, s28
	s_addc_u32 s47, s41, s29
	s_lshl_b64 s[28:29], s[44:45], 1
	s_add_u32 s44, s46, s28
	s_addc_u32 s45, s47, s29
	s_sub_i32 s28, s52, s24
	s_ashr_i32 s29, s28, 31
	s_lshl_b64 s[28:29], s[28:29], 1
	s_add_u32 s28, s44, s28
	s_addc_u32 s29, s45, s29
	v_mov_b32_e32 v145, v133
	s_mov_b32 s25, 0
	s_waitcnt vmcnt(0)
	v_pk_mul_f32 v[130:131], v[146:147], v[112:113]
	v_pk_mul_f32 v[150:151], v[148:149], v[114:115]
	v_cvt_pk_bf16_f32 v130, v130, v131
	v_cvt_pk_bf16_f32 v131, v150, v151
	ds_write_b64 v132, v[130:131]
	v_pk_mul_f32 v[130:131], v[146:147], v[48:49]
	v_pk_mul_f32 v[146:147], v[148:149], v[50:51]
	v_cvt_pk_bf16_f32 v130, v130, v131
	v_cvt_pk_bf16_f32 v131, v146, v147
	global_load_dwordx4 v[146:149], v[128:129], off offset:32
	v_add_u32_e32 v132, v204, v155
	ds_write_b64 v132, v[130:131] offset:16384
	v_add_u32_e32 v132, v204, v156
	s_waitcnt vmcnt(0)
	v_pk_mul_f32 v[130:131], v[146:147], v[116:117]
	v_pk_mul_f32 v[150:151], v[148:149], v[118:119]
	v_cvt_pk_bf16_f32 v130, v130, v131
	v_cvt_pk_bf16_f32 v131, v150, v151
	ds_write_b64 v132, v[130:131]
	v_pk_mul_f32 v[130:131], v[146:147], v[52:53]
	v_pk_mul_f32 v[146:147], v[148:149], v[54:55]
	v_cvt_pk_bf16_f32 v130, v130, v131
	v_cvt_pk_bf16_f32 v131, v146, v147
	global_load_dwordx4 v[146:149], v[128:129], off offset:64
	v_add_u32_e32 v132, v204, v157
	ds_write_b64 v132, v[130:131] offset:16384
	v_add_u32_e32 v132, v204, v158
	s_waitcnt vmcnt(0)
	v_pk_mul_f32 v[130:131], v[146:147], v[120:121]
	v_pk_mul_f32 v[150:151], v[148:149], v[122:123]
	v_cvt_pk_bf16_f32 v130, v130, v131
	v_cvt_pk_bf16_f32 v131, v150, v151
	ds_write_b64 v132, v[130:131]
	v_pk_mul_f32 v[130:131], v[146:147], v[56:57]
	v_pk_mul_f32 v[146:147], v[148:149], v[58:59]
	v_cvt_pk_bf16_f32 v130, v130, v131
	v_cvt_pk_bf16_f32 v131, v146, v147
	global_load_dwordx4 v[146:149], v[128:129], off offset:96
	v_add_u32_e32 v132, v204, v159
	ds_write_b64 v132, v[130:131] offset:16384
	v_add_u32_e32 v132, v204, v160
	s_waitcnt vmcnt(0)
	v_pk_mul_f32 v[130:131], v[146:147], v[124:125]
	v_pk_mul_f32 v[150:151], v[148:149], v[126:127]
	v_cvt_pk_bf16_f32 v130, v130, v131
	v_cvt_pk_bf16_f32 v131, v150, v151
	ds_write_b64 v132, v[130:131]
	v_pk_mul_f32 v[130:131], v[146:147], v[60:61]
	v_pk_mul_f32 v[146:147], v[148:149], v[62:63]
	v_cvt_pk_bf16_f32 v130, v130, v131
	v_cvt_pk_bf16_f32 v131, v146, v147
	global_load_dwordx4 v[146:149], v[128:129], off offset:128
	v_add_u32_e32 v132, v204, v161
	ds_write_b64 v132, v[130:131] offset:16384
	v_add_u32_e32 v132, v204, v162
	s_waitcnt vmcnt(0)
	v_pk_mul_f32 v[130:131], v[146:147], v[96:97]
	v_pk_mul_f32 v[150:151], v[148:149], v[98:99]
	v_cvt_pk_bf16_f32 v130, v130, v131
	v_cvt_pk_bf16_f32 v131, v150, v151
	ds_write_b64 v132, v[130:131]
	v_pk_mul_f32 v[130:131], v[146:147], v[32:33]
	v_pk_mul_f32 v[146:147], v[148:149], v[34:35]
	v_cvt_pk_bf16_f32 v130, v130, v131
	v_cvt_pk_bf16_f32 v131, v146, v147
	global_load_dwordx4 v[146:149], v[128:129], off offset:160
	v_add_u32_e32 v132, v204, v163
	ds_write_b64 v132, v[130:131] offset:16384
	v_add_u32_e32 v132, v204, v164
	s_waitcnt vmcnt(0)
	v_pk_mul_f32 v[130:131], v[146:147], v[100:101]
	v_pk_mul_f32 v[150:151], v[148:149], v[102:103]
	v_cvt_pk_bf16_f32 v130, v130, v131
	v_cvt_pk_bf16_f32 v131, v150, v151
	ds_write_b64 v132, v[130:131]
	v_pk_mul_f32 v[130:131], v[146:147], v[36:37]
	v_pk_mul_f32 v[146:147], v[148:149], v[38:39]
	v_cvt_pk_bf16_f32 v130, v130, v131
	v_cvt_pk_bf16_f32 v131, v146, v147
	global_load_dwordx4 v[146:149], v[128:129], off offset:192
	v_add_u32_e32 v132, v204, v165
	ds_write_b64 v132, v[130:131] offset:16384
	v_add_u32_e32 v132, v204, v166
	s_waitcnt vmcnt(0)
	v_pk_mul_f32 v[130:131], v[146:147], v[104:105]
	v_pk_mul_f32 v[150:151], v[148:149], v[106:107]
	v_cvt_pk_bf16_f32 v130, v130, v131
	v_cvt_pk_bf16_f32 v131, v150, v151
	ds_write_b64 v132, v[130:131]
	v_pk_mul_f32 v[130:131], v[146:147], v[40:41]
	v_pk_mul_f32 v[146:147], v[148:149], v[42:43]
	v_cvt_pk_bf16_f32 v130, v130, v131
	v_cvt_pk_bf16_f32 v131, v146, v147
	global_load_dwordx4 v[146:149], v[128:129], off offset:224
	v_add_u32_e32 v132, v204, v167
	ds_write_b64 v132, v[130:131] offset:16384
	v_add_u32_e32 v132, v204, v168
	s_waitcnt vmcnt(0)
	v_pk_mul_f32 v[130:131], v[146:147], v[108:109]
	v_pk_mul_f32 v[150:151], v[148:149], v[110:111]
	v_cvt_pk_bf16_f32 v130, v130, v131
	v_cvt_pk_bf16_f32 v131, v150, v151
	ds_write_b64 v132, v[130:131]
	v_pk_mul_f32 v[130:131], v[146:147], v[44:45]
	v_pk_mul_f32 v[146:147], v[148:149], v[46:47]
	v_cvt_pk_bf16_f32 v130, v130, v131
	v_cvt_pk_bf16_f32 v131, v146, v147
	global_load_dwordx4 v[146:149], v[128:129], off offset:256
	v_add_u32_e32 v132, v204, v169
	ds_write_b64 v132, v[130:131] offset:16384
	v_add_u32_e32 v132, v204, v170
	s_waitcnt vmcnt(0)
	v_pk_mul_f32 v[130:131], v[146:147], v[80:81]
	v_pk_mul_f32 v[150:151], v[148:149], v[82:83]
	v_cvt_pk_bf16_f32 v130, v130, v131
	v_cvt_pk_bf16_f32 v131, v150, v151
	ds_write_b64 v132, v[130:131]
	v_pk_mul_f32 v[130:131], v[146:147], v[0:1]
	v_pk_mul_f32 v[146:147], v[148:149], v[2:3]
	v_cvt_pk_bf16_f32 v130, v130, v131
	v_cvt_pk_bf16_f32 v131, v146, v147
	global_load_dwordx4 v[146:149], v[128:129], off offset:288
	v_add_u32_e32 v132, v204, v171
	ds_write_b64 v132, v[130:131] offset:16384
	v_add_u32_e32 v132, v204, v172
	s_waitcnt vmcnt(0)
	v_pk_mul_f32 v[130:131], v[146:147], v[84:85]
	v_pk_mul_f32 v[150:151], v[148:149], v[86:87]
	v_cvt_pk_bf16_f32 v130, v130, v131
	v_cvt_pk_bf16_f32 v131, v150, v151
	ds_write_b64 v132, v[130:131]
	v_pk_mul_f32 v[130:131], v[146:147], v[4:5]
	v_pk_mul_f32 v[146:147], v[148:149], v[6:7]
	v_cvt_pk_bf16_f32 v130, v130, v131
	v_cvt_pk_bf16_f32 v131, v146, v147
	global_load_dwordx4 v[146:149], v[128:129], off offset:320
	v_add_u32_e32 v132, v204, v173
	ds_write_b64 v132, v[130:131] offset:16384
	v_add_u32_e32 v132, v204, v174
	s_waitcnt vmcnt(0)
	v_pk_mul_f32 v[130:131], v[146:147], v[88:89]
	v_pk_mul_f32 v[150:151], v[148:149], v[90:91]
	v_cvt_pk_bf16_f32 v130, v130, v131
	v_cvt_pk_bf16_f32 v131, v150, v151
	ds_write_b64 v132, v[130:131]
	v_pk_mul_f32 v[130:131], v[146:147], v[8:9]
	v_pk_mul_f32 v[146:147], v[148:149], v[10:11]
	v_cvt_pk_bf16_f32 v130, v130, v131
	v_cvt_pk_bf16_f32 v131, v146, v147
	global_load_dwordx4 v[146:149], v[128:129], off offset:352
	v_add_u32_e32 v132, v204, v175
	ds_write_b64 v132, v[130:131] offset:16384
	v_add_u32_e32 v132, v204, v176
	s_waitcnt vmcnt(0)
	v_pk_mul_f32 v[130:131], v[146:147], v[92:93]
	v_pk_mul_f32 v[150:151], v[148:149], v[94:95]
	v_cvt_pk_bf16_f32 v130, v130, v131
	v_cvt_pk_bf16_f32 v131, v150, v151
	ds_write_b64 v132, v[130:131]
	v_pk_mul_f32 v[130:131], v[146:147], v[12:13]
	v_pk_mul_f32 v[146:147], v[148:149], v[14:15]
	v_cvt_pk_bf16_f32 v130, v130, v131
	v_cvt_pk_bf16_f32 v131, v146, v147
	global_load_dwordx4 v[146:149], v[128:129], off offset:384
	v_add_u32_e32 v132, v204, v177
	ds_write_b64 v132, v[130:131] offset:16384
	v_add_u32_e32 v132, v204, v178
	s_waitcnt vmcnt(0)
	v_pk_mul_f32 v[130:131], v[146:147], v[64:65]
	v_pk_mul_f32 v[150:151], v[148:149], v[66:67]
	v_cvt_pk_bf16_f32 v130, v130, v131
	v_cvt_pk_bf16_f32 v131, v150, v151
	ds_write_b64 v132, v[130:131]
	v_pk_mul_f32 v[130:131], v[146:147], v[16:17]
	v_pk_mul_f32 v[146:147], v[148:149], v[18:19]
	v_cvt_pk_bf16_f32 v130, v130, v131
	v_cvt_pk_bf16_f32 v131, v146, v147
	global_load_dwordx4 v[146:149], v[128:129], off offset:416
	v_add_u32_e32 v132, v204, v179
	ds_write_b64 v132, v[130:131] offset:16384
	v_add_u32_e32 v132, v204, v180
	s_waitcnt vmcnt(0)
	v_pk_mul_f32 v[130:131], v[146:147], v[68:69]
	v_pk_mul_f32 v[150:151], v[148:149], v[70:71]
	v_cvt_pk_bf16_f32 v130, v130, v131
	v_cvt_pk_bf16_f32 v131, v150, v151
	ds_write_b64 v132, v[130:131]
	v_pk_mul_f32 v[130:131], v[146:147], v[20:21]
	v_pk_mul_f32 v[146:147], v[148:149], v[22:23]
	v_cvt_pk_bf16_f32 v130, v130, v131
	v_cvt_pk_bf16_f32 v131, v146, v147
	global_load_dwordx4 v[146:149], v[128:129], off offset:448
	v_add_u32_e32 v132, v204, v181
	ds_write_b64 v132, v[130:131] offset:16384
	v_add_u32_e32 v132, v204, v182
	s_waitcnt vmcnt(0)
	v_pk_mul_f32 v[130:131], v[146:147], v[72:73]
	v_pk_mul_f32 v[150:151], v[148:149], v[74:75]
	v_cvt_pk_bf16_f32 v130, v130, v131
	v_cvt_pk_bf16_f32 v131, v150, v151
	ds_write_b64 v132, v[130:131]
	v_pk_mul_f32 v[130:131], v[146:147], v[24:25]
	v_pk_mul_f32 v[146:147], v[148:149], v[26:27]
	v_cvt_pk_bf16_f32 v130, v130, v131
	v_cvt_pk_bf16_f32 v131, v146, v147
	v_add_u32_e32 v132, v204, v183
	ds_write_b64 v132, v[130:131] offset:16384
	global_load_dwordx4 v[128:131], v[128:129], off offset:480
	v_add_u32_e32 v132, v204, v184
	s_waitcnt vmcnt(0)
	v_pk_mul_f32 v[146:147], v[128:129], v[76:77]
	v_pk_mul_f32 v[148:149], v[130:131], v[78:79]
	v_pk_mul_f32 v[128:129], v[128:129], v[28:29]
	v_pk_mul_f32 v[130:131], v[130:131], v[30:31]
	v_cvt_pk_bf16_f32 v146, v146, v147
	v_cvt_pk_bf16_f32 v147, v148, v149
	v_cvt_pk_bf16_f32 v128, v128, v129
	v_cvt_pk_bf16_f32 v129, v130, v131
	v_add_u32_e32 v130, v204, v185
	ds_write_b64 v132, v[146:147]
	ds_write_b64 v130, v[128:129] offset:16384
	v_lshl_add_u64 v[128:129], s[28:29], 0, v[144:145]
	v_mov_b64_e32 v[130:131], v[134:135]
	v_mov_b32_e32 v132, v206
	v_mov_b64_e32 v[146:147], v[142:143]
	s_waitcnt lgkmcnt(0)
	s_barrier

.LBB0_307:
	s_andn2_b64 vcc, exec, s[2:3]
	s_cbranch_vccnz .Lattn_fast
	s_add_i32 s16, s28, 0xfffffe00
	s_ashr_i32 s22, s28, 8
	s_lshr_b32 s8, s28, 2
	s_and_b32 s9, s28, 3
	s_lshr_b32 s16, s16, 7
	s_add_i32 s22, s22, 8
	s_cmpk_lt_i32 s28, 0x200
	s_cselect_b32 s24, 5, 4
	s_cselect_b32 s23, 31, 15
	s_cselect_b32 s16, s22, s16
	s_lshr_b32 s26, s28, s24
	s_and_b32 s8, s8, s23
	s_and_b32 s30, s26, 4
	s_or_b32 s27, s30, s9
	s_lshl_b32 s9, s16, 13
	s_lshl_b32 s8, s8, 8
	s_add_i32 s22, s9, 0xffff8000
	s_lshl_b32 s23, s16, 12
	s_add_i32 s29, s8, s18
	s_cmp_lt_i32 s16, 8
	s_cselect_b64 s[24:25], -1, 0
	s_and_b64 s[8:9], s[24:25], exec
	s_cselect_b32 s8, s23, s22
	s_cselect_b32 s31, 12, 13
	s_add_i32 s29, s29, s8
	v_or_b32_e32 v0, s29, v189
	v_ashrrev_i32_e32 v1, 31, v0
	v_lshlrev_b64 v[0:1], 10, v[0:1]
	v_lshl_add_u64 v[0:1], s[62:63], 0, v[0:1]
	s_lshl_b32 s16, s27, 7
	v_lshl_add_u64 v[0:1], v[0:1], 0, s[16:17]
	v_lshlrev_b32_e32 v98, 1, v196
	v_lshl_add_u64 v[8:9], v[0:1], 0, v[98:99]
	v_or_b32_e32 v0, s8, v148
	v_ashrrev_i32_e32 v1, 31, v0
	s_ashr_i32 s9, s8, 31
	v_lshlrev_b64 v[138:139], 8, v[0:1]
	s_lshl_b32 s16, s30, 5
	s_lshl_b64 s[22:23], s[8:9], 8
	v_lshl_add_u64 v[0:1], s[64:65], 0, v[138:139]
	v_lshl_add_u32 v98, s30, 4, v148
	s_add_u32 s8, s72, s22
	v_lshl_add_u64 v[0:1], v[0:1], 0, s[16:17]
	v_mov_b32_e32 v137, v99
	s_addc_u32 s9, s73, s23
	v_lshlrev_b64 v[140:141], s31, v[98:99]
	v_lshl_add_u64 v[10:11], v[0:1], 0, v[136:137]
	v_lshl_add_u64 v[0:1], v[140:141], 1, s[8:9]
	v_lshl_add_u64 v[12:13], v[0:1], 0, v[136:137]
	global_load_dwordx4 v[0:3], v[10:11], off
	global_load_dwordx4 v[4:7], v[12:13], off
	global_load_dwordx4 v[74:77], v[8:9], off
	global_load_dwordx4 v[78:81], v[8:9], off offset:32
	global_load_dwordx4 v[82:85], v[8:9], off offset:64
	global_load_dwordx4 v[86:89], v[8:9], off offset:96
	v_add_co_u32_e32 v8, vcc, s11, v10
	v_add_u32_e32 v186, v151, v157
	s_nop 0
	v_addc_co_u32_e32 v9, vcc, 0, v11, vcc
	v_add_u32_e32 v185, v151, v158
	v_add_u32_e32 v137, v151, v159
	s_waitcnt vmcnt(5)
	ds_write_b128 v150, v[0:3]
	s_waitcnt vmcnt(4)
	ds_write_b128 v150, v[4:7] offset:8192
	s_waitcnt lgkmcnt(0)
	s_barrier
	global_load_dwordx4 v[90:93], v[8:9], off
	global_load_dwordx4 v[94:97], v[12:13], off offset:128
	v_add_u32_e32 v0, v151, v156
	ds_read_b128 v[2:5], v0
	ds_read_b128 v[6:9], v0 offset:4096
	ds_read_b128 v[10:13], v186
	ds_read_b128 v[14:17], v186 offset:4096
	ds_read_b128 v[18:21], v185
	ds_read_b128 v[22:25], v185 offset:4096
	ds_read_b128 v[42:45], v137
	ds_read_b128 v[46:49], v137 offset:4096
	s_waitcnt vmcnt(5) lgkmcnt(7)
	v_mfma_f32_32x32x16_bf16 v[58:73], v[2:5], v[74:77], 0
	v_cndmask_b32_e64 v1, 0, 1, s[2:3]
	v_mov_b32_e32 v98, 0
	v_cmp_ne_u32_e64 s[8:9], 1, v1
	s_andn2_b64 vcc, exec, s[2:3]
	s_waitcnt lgkmcnt(6)
	v_mfma_f32_32x32x16_bf16 v[26:41], v[6:9], v[74:77], 0
	s_waitcnt vmcnt(4) lgkmcnt(5)
	v_mfma_f32_32x32x16_bf16 v[58:73], v[10:13], v[78:81], v[58:73]
	s_waitcnt lgkmcnt(4)
	v_mfma_f32_32x32x16_bf16 v[26:41], v[14:17], v[78:81], v[26:41]
	s_waitcnt vmcnt(3) lgkmcnt(3)
	v_mfma_f32_32x32x16_bf16 v[58:73], v[18:21], v[82:85], v[58:73]
	s_waitcnt lgkmcnt(2)
	v_mfma_f32_32x32x16_bf16 v[26:41], v[22:25], v[82:85], v[26:41]
	s_waitcnt vmcnt(2) lgkmcnt(1)
	v_mfma_f32_32x32x16_bf16 v[58:73], v[42:45], v[86:89], v[58:73]
	s_waitcnt lgkmcnt(0)
	v_mfma_f32_32x32x16_bf16 v[26:41], v[46:49], v[86:89], v[26:41]
	s_cbranch_vccnz .LBB0_309
	s_nop 8
	v_max3_f32 v1, v58, v59, v60
	s_nop 0
	v_max3_f32 v2, v26, v27, v28
	v_max3_f32 v1, v1, v61, v62
	v_max3_f32 v2, v2, v29, v30
	v_max3_f32 v1, v1, v63, v64
	v_max3_f32 v2, v2, v31, v32
	v_max3_f32 v1, v1, v65, v66
	v_max3_f32 v2, v2, v33, v34
	v_max3_f32 v1, v1, v67, v68
	v_max3_f32 v2, v2, v35, v36
	v_max3_f32 v1, v1, v69, v70
	v_max3_f32 v2, v2, v37, v38
	v_max_f32_e32 v3, v41, v41
	v_max_f32_e32 v4, v73, v73
	v_max3_f32 v1, v1, v71, v72
	v_max3_f32 v2, v2, v39, v40
	v_max_f32_e32 v3, v4, v3
	v_max3_f32 v1, v1, v2, v3
	v_mov_b32_e32 v2, v1
	s_nop 1
	v_permlane32_swap_b32_e32 v1, v2
	v_max_f32_e32 v2, v2, v2
	v_max_f32_e32 v1, v1, v1
	v_max_f32_e32 v1, v1, v2
	v_exp_f32_e64 v2, -v1
	v_sub_f32_e32 v73, v73, v1
	v_sub_f32_e32 v72, v72, v1
	v_sub_f32_e32 v71, v71, v1
	v_mul_f32_e32 v42, 0, v2
	v_sub_f32_e32 v70, v70, v1
	v_sub_f32_e32 v69, v69, v1
	v_sub_f32_e32 v68, v68, v1
	v_sub_f32_e32 v67, v67, v1
	v_sub_f32_e32 v66, v66, v1
	v_sub_f32_e32 v65, v65, v1
	v_sub_f32_e32 v64, v64, v1
	v_sub_f32_e32 v63, v63, v1
	v_sub_f32_e32 v62, v62, v1
	v_sub_f32_e32 v61, v61, v1
	v_sub_f32_e32 v60, v60, v1
	v_sub_f32_e32 v59, v59, v1
	v_sub_f32_e32 v58, v58, v1
	v_sub_f32_e32 v41, v41, v1
	v_sub_f32_e32 v40, v40, v1
	v_sub_f32_e32 v39, v39, v1
	v_sub_f32_e32 v38, v38, v1
	v_sub_f32_e32 v37, v37, v1
	v_sub_f32_e32 v36, v36, v1
	v_sub_f32_e32 v35, v35, v1
	v_sub_f32_e32 v34, v34, v1
	v_sub_f32_e32 v33, v33, v1
	v_sub_f32_e32 v32, v32, v1
	v_sub_f32_e32 v31, v31, v1
	v_sub_f32_e32 v30, v30, v1
	v_sub_f32_e32 v29, v29, v1
	v_sub_f32_e32 v28, v28, v1
	v_sub_f32_e32 v27, v27, v1
	v_sub_f32_e32 v26, v26, v1
	v_add_f32_e32 v98, 0, v1
	s_branch .LBB0_310

.Lattn_fast:
	s_add_i32 s16, s28, 0xfffffe00
	s_ashr_i32 s22, s28, 8
	s_lshr_b32 s8, s28, 2
	s_and_b32 s9, s28, 3
	s_lshr_b32 s16, s16, 7
	s_add_i32 s22, s22, 8
	s_cmpk_lt_i32 s28, 0x200
	s_cselect_b32 s24, 5, 4
	s_cselect_b32 s23, 31, 15
	s_cselect_b32 s16, s22, s16
	s_lshr_b32 s26, s28, s24
	s_and_b32 s8, s8, s23
	s_and_b32 s30, s26, 4
	s_or_b32 s27, s30, s9
	s_lshl_b32 s9, s16, 13
	s_lshl_b32 s8, s8, 8
	s_add_i32 s22, s9, 0xffff8000
	s_lshl_b32 s23, s16, 12
	s_add_i32 s29, s8, s18
	s_cmp_lt_i32 s16, 8
	s_cselect_b32 s8, s23, s22
	s_cselect_b32 s31, 12, 13
	s_add_i32 s29, s29, s8
	v_or_b32_e32 v0, s29, v189
	v_ashrrev_i32_e32 v1, 31, v0
	v_lshlrev_b64 v[0:1], 10, v[0:1]
	v_lshl_add_u64 v[0:1], s[62:63], 0, v[0:1]
	s_lshl_b32 s16, s27, 7
	v_lshl_add_u64 v[0:1], v[0:1], 0, s[16:17]
	v_lshlrev_b32_e32 v98, 1, v196
	v_lshl_add_u64 v[8:9], v[0:1], 0, v[98:99]
	s_lshl_b32 s26, s8, 8
	s_lshl_b32 s9, s30, 5
	s_add_u32 s9, s26, s9
	s_add_u32 s22, s64, s9
	s_addc_u32 s23, s65, 0
	s_add_i32 s9, s31, 5
	s_lshl_b32 s9, s30, s9
	s_add_u32 s9, s26, s9
	s_add_u32 s24, s72, s9
	s_addc_u32 s25, s73, 0
	v_lshl_add_u32 v210, v148, 8, v136
	s_add_i32 s9, s31, 1
	v_lshlrev_b32_e32 v211, s9, v148
	v_add_u32_e32 v211, v211, v136
	v_add_u32_e32 v206, v151, v156
	v_add_u32_e32 v207, v151, v157
	v_add_u32_e32 v208, v151, v158
	v_add_u32_e32 v209, v151, v159
	s_lshl_b32 s30, s27, 6
	s_lshl_b32 s33, 1, s31
	s_lshr_b32 s33, s33, 6
	s_add_i32 s16, s33, -1
	s_lshr_b32 s33, s33, 2
	s_mov_b32 s31, 5
	global_load_dwordx4 v[32:35], v210, s[22:23]
	s_add_u32 s26, s22, 0x4000
	s_addc_u32 s27, s23, 0
	global_load_dwordx4 v[36:39], v210, s[26:27]
	s_add_u32 s8, s22, 0x8000
	s_addc_u32 s9, s23, 0
	global_load_dwordx4 v[40:43], v210, s[8:9]
	global_load_dwordx4 v[44:47], v211, s[24:25]
	global_load_dwordx4 v[48:51], v211, s[24:25] offset:128
	global_load_dwordx4 v[74:77], v[8:9], off
	global_load_dwordx4 v[78:81], v[8:9], off offset:32
	global_load_dwordx4 v[82:85], v[8:9], off offset:64
	global_load_dwordx4 v[86:89], v[8:9], off offset:96
	s_add_u32 s26, s22, 0xc000
	s_addc_u32 s27, s23, 0
	global_load_dwordx4 v[90:93], v210, s[26:27]
	global_load_dwordx4 v[94:97], v211, s[24:25] offset:256
	s_add_u32 s8, s22, 0x10000
	s_addc_u32 s9, s23, 0
	global_load_dwordx4 v[250:253], v210, s[8:9]
	global_load_dwordx4 v[138:141], v211, s[24:25] offset:384
	v_mov_b32_e32 v72, 0
	v_mov_b32_e32 v73, 0
	v_mov_b32_e32 v16, 0
	v_mov_b32_e32 v17, 0
	v_mov_b32_e32 v18, 0
	v_mov_b32_e32 v19, 0
	v_mov_b32_e32 v20, 0
	v_mov_b32_e32 v21, 0
	v_mov_b32_e32 v22, 0
	v_mov_b32_e32 v23, 0
	v_mov_b32_e32 v24, 0
	v_mov_b32_e32 v25, 0
	v_mov_b32_e32 v26, 0
	v_mov_b32_e32 v27, 0
	v_mov_b32_e32 v28, 0
	v_mov_b32_e32 v29, 0
	v_mov_b32_e32 v30, 0
	v_mov_b32_e32 v31, 0
	v_mov_b32_e32 v0, 0
	v_mov_b32_e32 v1, 0
	v_mov_b32_e32 v2, 0
	v_mov_b32_e32 v3, 0
	v_mov_b32_e32 v4, 0
	v_mov_b32_e32 v5, 0
	v_mov_b32_e32 v6, 0
	v_mov_b32_e32 v7, 0
	v_mov_b32_e32 v8, 0
	v_mov_b32_e32 v9, 0
	v_mov_b32_e32 v10, 0
	v_mov_b32_e32 v11, 0
	v_mov_b32_e32 v12, 0
	v_mov_b32_e32 v13, 0
	v_mov_b32_e32 v14, 0
	v_mov_b32_e32 v15, 0
	s_waitcnt vmcnt(12)
	ds_write_b128 v150, v[32:35]
	s_waitcnt vmcnt(11)
	ds_write_b128 v150, v[36:39] offset:16384
	s_waitcnt vmcnt(10)
	ds_write_b128 v150, v[40:43] offset:32768
	s_waitcnt vmcnt(9)
	ds_write_b128 v150, v[44:47] offset:8192
	s_waitcnt vmcnt(8)
	ds_write_b128 v150, v[48:51] offset:24576
	s_waitcnt lgkmcnt(0)
	s_barrier
	ds_read_b128 v[218:221], v206
	ds_read_b128 v[226:229], v207
	ds_read_b128 v[234:237], v208
	s_waitcnt lgkmcnt(2)
	s_waitcnt vmcnt(7)
	v_mfma_f32_32x32x16_bf16 v[32:47], v[218:221], v[74:77], 0
	ds_read_b128 v[242:245], v209
	s_waitcnt lgkmcnt(2)
	s_waitcnt vmcnt(6)
	v_mfma_f32_32x32x16_bf16 v[32:47], v[226:229], v[78:81], v[32:47]
	ds_read_b128 v[218:221], v206 offset:4096
	s_waitcnt lgkmcnt(2)
	s_waitcnt vmcnt(5)
	v_mfma_f32_32x32x16_bf16 v[32:47], v[234:237], v[82:85], v[32:47]
	ds_read_b128 v[226:229], v207 offset:4096
	s_waitcnt lgkmcnt(2)
	s_waitcnt vmcnt(4)
	v_mfma_f32_32x32x16_bf16 v[32:47], v[242:245], v[86:89], v[32:47]
	ds_read_b128 v[234:237], v208 offset:4096
	s_nop 9
	s_waitcnt lgkmcnt(2)
	v_mfma_f32_32x32x16_bf16 v[48:63], v[218:221], v[74:77], 0
	ds_read_b128 v[242:245], v209 offset:4096
	v_exp_f32_e32 v32, v32
	v_exp_f32_e32 v33, v33
	v_add_f32_e32 v72, v72, v32
	v_add_f32_e32 v73, v73, v33
	v_cvt_pk_bf16_f32 v64, v32, v33
	v_exp_f32_e32 v34, v34
	v_exp_f32_e32 v35, v35
	v_add_f32_e32 v72, v72, v34
	v_add_f32_e32 v73, v73, v35
	v_cvt_pk_bf16_f32 v65, v34, v35
	s_waitcnt lgkmcnt(2)
	v_mfma_f32_32x32x16_bf16 v[48:63], v[226:229], v[78:81], v[48:63]
	ds_read_b128 v[218:221], v206 offset:16384
	v_exp_f32_e32 v36, v36
	v_exp_f32_e32 v37, v37
	v_add_f32_e32 v72, v72, v36
	v_add_f32_e32 v73, v73, v37
	v_cvt_pk_bf16_f32 v66, v36, v37
	ds_read_b128 v[222:225], v206 offset:8192
	v_exp_f32_e32 v38, v38
	v_exp_f32_e32 v39, v39
	v_add_f32_e32 v72, v72, v38
	v_add_f32_e32 v73, v73, v39
	v_cvt_pk_bf16_f32 v67, v38, v39
	s_waitcnt lgkmcnt(3)
	v_mfma_f32_32x32x16_bf16 v[48:63], v[234:237], v[82:85], v[48:63]
	ds_read_b128 v[226:229], v207 offset:16384
	v_exp_f32_e32 v40, v40
	v_exp_f32_e32 v41, v41
	v_add_f32_e32 v72, v72, v40
	v_add_f32_e32 v73, v73, v41
	v_cvt_pk_bf16_f32 v68, v40, v41
	ds_read_b128 v[230:233], v206 offset:12288
	v_exp_f32_e32 v42, v42
	v_exp_f32_e32 v43, v43
	v_add_f32_e32 v72, v72, v42
	v_add_f32_e32 v73, v73, v43
	v_cvt_pk_bf16_f32 v69, v42, v43
	s_waitcnt lgkmcnt(4)
	v_mfma_f32_32x32x16_bf16 v[48:63], v[242:245], v[86:89], v[48:63]
	ds_read_b128 v[234:237], v208 offset:16384
	v_exp_f32_e32 v44, v44
	v_exp_f32_e32 v45, v45
	v_add_f32_e32 v72, v72, v44
	v_add_f32_e32 v73, v73, v45
	v_cvt_pk_bf16_f32 v70, v44, v45
	ds_read_b128 v[238:241], v207 offset:8192
	v_exp_f32_e32 v46, v46
	v_exp_f32_e32 v47, v47
	v_add_f32_e32 v72, v72, v46
	v_add_f32_e32 v73, v73, v47
	v_cvt_pk_bf16_f32 v71, v46, v47
.Lattn_loop:
	s_waitcnt lgkmcnt(5)
	v_mfma_f32_32x32x16_bf16 v[32:47], v[218:221], v[74:77], 0
	ds_read_b128 v[242:245], v209 offset:16384
	v_exp_f32_e32 v48, v48
	v_exp_f32_e32 v49, v49
	v_add_f32_e32 v72, v72, v48
	v_add_f32_e32 v73, v73, v49
	v_cvt_pk_bf16_f32 v198, v48, v49
	s_waitcnt lgkmcnt(5)
	v_mfma_f32_32x32x16_bf16 v[16:31], v[222:225], v[64:67], v[16:31]
	ds_read_b128 v[246:249], v207 offset:12288
	s_waitcnt vmcnt(3)
	ds_write_b128 v150, v[90:93] offset:49152
	s_waitcnt vmcnt(2)
	ds_write_b128 v150, v[94:97] offset:40960
	v_exp_f32_e32 v50, v50
	v_exp_f32_e32 v51, v51
	v_add_f32_e32 v72, v72, v50
	v_add_f32_e32 v73, v73, v51
	v_cvt_pk_bf16_f32 v199, v50, v51
	s_waitcnt lgkmcnt(7)
	v_mfma_f32_32x32x16_bf16 v[32:47], v[226:229], v[78:81], v[32:47]
	ds_read_b128 v[218:221], v206 offset:20480
	v_exp_f32_e32 v52, v52
	v_exp_f32_e32 v53, v53
	v_add_f32_e32 v72, v72, v52
	v_add_f32_e32 v73, v73, v53
	v_cvt_pk_bf16_f32 v200, v52, v53
	s_waitcnt lgkmcnt(7)
	v_mfma_f32_32x32x16_bf16 v[0:15], v[230:233], v[64:67], v[0:15]
	ds_read_b128 v[222:225], v208 offset:8192
	s_min_u32 s8, s31, s16
	s_lshl_b32 s8, s8, 14
	s_add_u32 s26, s22, s8
	s_addc_u32 s27, s23, 0
	global_load_dwordx4 v[90:93], v210, s[26:27]
	s_add_i32 s9, s31, -1
	s_min_u32 s9, s9, s16
	s_lshl_b32 s9, s9, 7
	s_add_u32 s8, s24, s9
	s_addc_u32 s9, s25, 0
	global_load_dwordx4 v[94:97], v211, s[8:9]
	s_add_i32 s31, s31, 1
	v_exp_f32_e32 v54, v54
	v_exp_f32_e32 v55, v55
	v_add_f32_e32 v72, v72, v54
	v_add_f32_e32 v73, v73, v55
	v_cvt_pk_bf16_f32 v201, v54, v55
	s_waitcnt lgkmcnt(7)
	v_mfma_f32_32x32x16_bf16 v[32:47], v[234:237], v[82:85], v[32:47]
	ds_read_b128 v[226:229], v207 offset:20480
	v_exp_f32_e32 v56, v56
	v_exp_f32_e32 v57, v57
	v_add_f32_e32 v72, v72, v56
	v_add_f32_e32 v73, v73, v57
	v_cvt_pk_bf16_f32 v202, v56, v57
	s_waitcnt lgkmcnt(7)
	v_mfma_f32_32x32x16_bf16 v[16:31], v[238:241], v[68:71], v[16:31]
	ds_read_b128 v[230:233], v208 offset:12288
	v_exp_f32_e32 v58, v58
	v_exp_f32_e32 v59, v59
	v_add_f32_e32 v72, v72, v58
	v_add_f32_e32 v73, v73, v59
	v_cvt_pk_bf16_f32 v203, v58, v59
	s_waitcnt lgkmcnt(7)
	v_mfma_f32_32x32x16_bf16 v[32:47], v[242:245], v[86:89], v[32:47]
	ds_read_b128 v[234:237], v208 offset:20480
	v_exp_f32_e32 v60, v60
	v_exp_f32_e32 v61, v61
	v_add_f32_e32 v72, v72, v60
	v_add_f32_e32 v73, v73, v61
	v_cvt_pk_bf16_f32 v204, v60, v61
	s_waitcnt lgkmcnt(7)
	v_mfma_f32_32x32x16_bf16 v[0:15], v[246:249], v[68:71], v[0:15]
	ds_read_b128 v[238:241], v209 offset:8192
	v_exp_f32_e32 v62, v62
	v_exp_f32_e32 v63, v63
	v_add_f32_e32 v72, v72, v62
	v_add_f32_e32 v73, v73, v63
	v_cvt_pk_bf16_f32 v205, v62, v63
	s_waitcnt lgkmcnt(5)
	v_mfma_f32_32x32x16_bf16 v[48:63], v[218:221], v[74:77], 0
	ds_read_b128 v[242:245], v209 offset:20480
	v_exp_f32_e32 v32, v32
	v_exp_f32_e32 v33, v33
	v_add_f32_e32 v72, v72, v32
	v_add_f32_e32 v73, v73, v33
	v_cvt_pk_bf16_f32 v64, v32, v33
	s_waitcnt lgkmcnt(5)
	v_mfma_f32_32x32x16_bf16 v[16:31], v[222:225], v[198:201], v[16:31]
	ds_read_b128 v[246:249], v209 offset:12288
	v_exp_f32_e32 v34, v34
	v_exp_f32_e32 v35, v35
	v_add_f32_e32 v72, v72, v34
	v_add_f32_e32 v73, v73, v35
	v_cvt_pk_bf16_f32 v65, v34, v35
	s_waitcnt lgkmcnt(5)
	v_mfma_f32_32x32x16_bf16 v[48:63], v[226:229], v[78:81], v[48:63]
	ds_read_b128 v[218:221], v206 offset:32768
	v_exp_f32_e32 v36, v36
	v_exp_f32_e32 v37, v37
	v_add_f32_e32 v72, v72, v36
	v_add_f32_e32 v73, v73, v37
	v_cvt_pk_bf16_f32 v66, v36, v37
	s_waitcnt lgkmcnt(5)
	v_mfma_f32_32x32x16_bf16 v[0:15], v[230:233], v[198:201], v[0:15]
	ds_read_b128 v[222:225], v206 offset:24576
	v_exp_f32_e32 v38, v38
	v_exp_f32_e32 v39, v39
	v_add_f32_e32 v72, v72, v38
	v_add_f32_e32 v73, v73, v39
	v_cvt_pk_bf16_f32 v67, v38, v39
	s_waitcnt lgkmcnt(5)
	v_mfma_f32_32x32x16_bf16 v[48:63], v[234:237], v[82:85], v[48:63]
	ds_read_b128 v[226:229], v207 offset:32768
	v_exp_f32_e32 v40, v40
	v_exp_f32_e32 v41, v41
	v_add_f32_e32 v72, v72, v40
	v_add_f32_e32 v73, v73, v41
	v_cvt_pk_bf16_f32 v68, v40, v41
	s_waitcnt lgkmcnt(5)
	v_mfma_f32_32x32x16_bf16 v[16:31], v[238:241], v[202:205], v[16:31]
	ds_read_b128 v[230:233], v206 offset:28672
	v_exp_f32_e32 v42, v42
	v_exp_f32_e32 v43, v43
	v_add_f32_e32 v72, v72, v42
	v_add_f32_e32 v73, v73, v43
	v_cvt_pk_bf16_f32 v69, v42, v43
	s_waitcnt lgkmcnt(5)
	v_mfma_f32_32x32x16_bf16 v[48:63], v[242:245], v[86:89], v[48:63]
	ds_read_b128 v[234:237], v208 offset:32768
	v_exp_f32_e32 v44, v44
	v_exp_f32_e32 v45, v45
	v_add_f32_e32 v72, v72, v44
	v_add_f32_e32 v73, v73, v45
	v_cvt_pk_bf16_f32 v70, v44, v45
	s_waitcnt lgkmcnt(5)
	v_mfma_f32_32x32x16_bf16 v[0:15], v[246:249], v[202:205], v[0:15]
	ds_read_b128 v[238:241], v207 offset:24576
	v_exp_f32_e32 v46, v46
	v_exp_f32_e32 v47, v47
	v_add_f32_e32 v72, v72, v46
	v_add_f32_e32 v73, v73, v47
	v_cvt_pk_bf16_f32 v71, v46, v47
	s_barrier
	s_waitcnt lgkmcnt(5)
	v_mfma_f32_32x32x16_bf16 v[32:47], v[218:221], v[74:77], 0
	ds_read_b128 v[242:245], v209 offset:32768
	v_exp_f32_e32 v48, v48
	v_exp_f32_e32 v49, v49
	v_add_f32_e32 v72, v72, v48
	v_add_f32_e32 v73, v73, v49
	v_cvt_pk_bf16_f32 v198, v48, v49
	s_waitcnt lgkmcnt(5)
	v_mfma_f32_32x32x16_bf16 v[16:31], v[222:225], v[64:67], v[16:31]
	ds_read_b128 v[246:249], v207 offset:28672
	s_waitcnt vmcnt(3)
	ds_write_b128 v150, v[250:253]
	s_waitcnt vmcnt(2)
	ds_write_b128 v150, v[138:141] offset:57344
	v_exp_f32_e32 v50, v50
	v_exp_f32_e32 v51, v51
	v_add_f32_e32 v72, v72, v50
	v_add_f32_e32 v73, v73, v51
	v_cvt_pk_bf16_f32 v199, v50, v51
	s_waitcnt lgkmcnt(7)
	v_mfma_f32_32x32x16_bf16 v[32:47], v[226:229], v[78:81], v[32:47]
	ds_read_b128 v[218:221], v206 offset:36864
	v_exp_f32_e32 v52, v52
	v_exp_f32_e32 v53, v53
	v_add_f32_e32 v72, v72, v52
	v_add_f32_e32 v73, v73, v53
	v_cvt_pk_bf16_f32 v200, v52, v53
	s_waitcnt lgkmcnt(7)
	v_mfma_f32_32x32x16_bf16 v[0:15], v[230:233], v[64:67], v[0:15]
	ds_read_b128 v[222:225], v208 offset:24576
	s_min_u32 s8, s31, s16
	s_lshl_b32 s8, s8, 14
	s_add_u32 s26, s22, s8
	s_addc_u32 s27, s23, 0
	global_load_dwordx4 v[250:253], v210, s[26:27]
	s_add_i32 s9, s31, -1
	s_min_u32 s9, s9, s16
	s_lshl_b32 s9, s9, 7
	s_add_u32 s8, s24, s9
	s_addc_u32 s9, s25, 0
	global_load_dwordx4 v[138:141], v211, s[8:9]
	s_add_i32 s31, s31, 1
	v_exp_f32_e32 v54, v54
	v_exp_f32_e32 v55, v55
	v_add_f32_e32 v72, v72, v54
	v_add_f32_e32 v73, v73, v55
	v_cvt_pk_bf16_f32 v201, v54, v55
	s_waitcnt lgkmcnt(7)
	v_mfma_f32_32x32x16_bf16 v[32:47], v[234:237], v[82:85], v[32:47]
	ds_read_b128 v[226:229], v207 offset:36864
	v_exp_f32_e32 v56, v56
	v_exp_f32_e32 v57, v57
	v_add_f32_e32 v72, v72, v56
	v_add_f32_e32 v73, v73, v57
	v_cvt_pk_bf16_f32 v202, v56, v57
	s_waitcnt lgkmcnt(7)
	v_mfma_f32_32x32x16_bf16 v[16:31], v[238:241], v[68:71], v[16:31]
	ds_read_b128 v[230:233], v208 offset:28672
	v_exp_f32_e32 v58, v58
	v_exp_f32_e32 v59, v59
	v_add_f32_e32 v72, v72, v58
	v_add_f32_e32 v73, v73, v59
	v_cvt_pk_bf16_f32 v203, v58, v59
	s_waitcnt lgkmcnt(7)
	v_mfma_f32_32x32x16_bf16 v[32:47], v[242:245], v[86:89], v[32:47]
	ds_read_b128 v[234:237], v208 offset:36864
	v_exp_f32_e32 v60, v60
	v_exp_f32_e32 v61, v61
	v_add_f32_e32 v72, v72, v60
	v_add_f32_e32 v73, v73, v61
	v_cvt_pk_bf16_f32 v204, v60, v61
	s_waitcnt lgkmcnt(7)
	v_mfma_f32_32x32x16_bf16 v[0:15], v[246:249], v[68:71], v[0:15]
	ds_read_b128 v[238:241], v209 offset:24576
	v_exp_f32_e32 v62, v62
	v_exp_f32_e32 v63, v63
	v_add_f32_e32 v72, v72, v62
	v_add_f32_e32 v73, v73, v63
	v_cvt_pk_bf16_f32 v205, v62, v63
	s_waitcnt lgkmcnt(5)
	v_mfma_f32_32x32x16_bf16 v[48:63], v[218:221], v[74:77], 0
	ds_read_b128 v[242:245], v209 offset:36864
	v_exp_f32_e32 v32, v32
	v_exp_f32_e32 v33, v33
	v_add_f32_e32 v72, v72, v32
	v_add_f32_e32 v73, v73, v33
	v_cvt_pk_bf16_f32 v64, v32, v33
	s_waitcnt lgkmcnt(5)
	v_mfma_f32_32x32x16_bf16 v[16:31], v[222:225], v[198:201], v[16:31]
	ds_read_b128 v[246:249], v209 offset:28672
	v_exp_f32_e32 v34, v34
	v_exp_f32_e32 v35, v35
	v_add_f32_e32 v72, v72, v34
	v_add_f32_e32 v73, v73, v35
	v_cvt_pk_bf16_f32 v65, v34, v35
	s_waitcnt lgkmcnt(5)
	v_mfma_f32_32x32x16_bf16 v[48:63], v[226:229], v[78:81], v[48:63]
	ds_read_b128 v[218:221], v206 offset:49152
	v_exp_f32_e32 v36, v36
	v_exp_f32_e32 v37, v37
	v_add_f32_e32 v72, v72, v36
	v_add_f32_e32 v73, v73, v37
	v_cvt_pk_bf16_f32 v66, v36, v37
	s_waitcnt lgkmcnt(5)
	v_mfma_f32_32x32x16_bf16 v[0:15], v[230:233], v[198:201], v[0:15]
	ds_read_b128 v[222:225], v206 offset:40960
	v_exp_f32_e32 v38, v38
	v_exp_f32_e32 v39, v39
	v_add_f32_e32 v72, v72, v38
	v_add_f32_e32 v73, v73, v39
	v_cvt_pk_bf16_f32 v67, v38, v39
	s_waitcnt lgkmcnt(5)
	v_mfma_f32_32x32x16_bf16 v[48:63], v[234:237], v[82:85], v[48:63]
	ds_read_b128 v[226:229], v207 offset:49152
	v_exp_f32_e32 v40, v40
	v_exp_f32_e32 v41, v41
	v_add_f32_e32 v72, v72, v40
	v_add_f32_e32 v73, v73, v41
	v_cvt_pk_bf16_f32 v68, v40, v41
	s_waitcnt lgkmcnt(5)
	v_mfma_f32_32x32x16_bf16 v[16:31], v[238:241], v[202:205], v[16:31]
	ds_read_b128 v[230:233], v206 offset:45056
	v_exp_f32_e32 v42, v42
	v_exp_f32_e32 v43, v43
	v_add_f32_e32 v72, v72, v42
	v_add_f32_e32 v73, v73, v43
	v_cvt_pk_bf16_f32 v69, v42, v43
	s_waitcnt lgkmcnt(5)
	v_mfma_f32_32x32x16_bf16 v[48:63], v[242:245], v[86:89], v[48:63]
	ds_read_b128 v[234:237], v208 offset:49152
	v_exp_f32_e32 v44, v44
	v_exp_f32_e32 v45, v45
	v_add_f32_e32 v72, v72, v44
	v_add_f32_e32 v73, v73, v45
	v_cvt_pk_bf16_f32 v70, v44, v45
	s_waitcnt lgkmcnt(5)
	v_mfma_f32_32x32x16_bf16 v[0:15], v[246:249], v[202:205], v[0:15]
	ds_read_b128 v[238:241], v207 offset:40960
	v_exp_f32_e32 v46, v46
	v_exp_f32_e32 v47, v47
	v_add_f32_e32 v72, v72, v46
	v_add_f32_e32 v73, v73, v47
	v_cvt_pk_bf16_f32 v71, v46, v47
	s_barrier
	s_waitcnt lgkmcnt(5)
	v_mfma_f32_32x32x16_bf16 v[32:47], v[218:221], v[74:77], 0
	ds_read_b128 v[242:245], v209 offset:49152
	v_exp_f32_e32 v48, v48
	v_exp_f32_e32 v49, v49
	v_add_f32_e32 v72, v72, v48
	v_add_f32_e32 v73, v73, v49
	v_cvt_pk_bf16_f32 v198, v48, v49
	s_waitcnt lgkmcnt(5)
	v_mfma_f32_32x32x16_bf16 v[16:31], v[222:225], v[64:67], v[16:31]
	ds_read_b128 v[246:249], v207 offset:45056
	s_waitcnt vmcnt(3)
	ds_write_b128 v150, v[90:93] offset:16384
	s_waitcnt vmcnt(2)
	ds_write_b128 v150, v[94:97] offset:8192
	v_exp_f32_e32 v50, v50
	v_exp_f32_e32 v51, v51
	v_add_f32_e32 v72, v72, v50
	v_add_f32_e32 v73, v73, v51
	v_cvt_pk_bf16_f32 v199, v50, v51
	s_waitcnt lgkmcnt(7)
	v_mfma_f32_32x32x16_bf16 v[32:47], v[226:229], v[78:81], v[32:47]
	ds_read_b128 v[218:221], v206 offset:53248
	v_exp_f32_e32 v52, v52
	v_exp_f32_e32 v53, v53
	v_add_f32_e32 v72, v72, v52
	v_add_f32_e32 v73, v73, v53
	v_cvt_pk_bf16_f32 v200, v52, v53
	s_waitcnt lgkmcnt(7)
	v_mfma_f32_32x32x16_bf16 v[0:15], v[230:233], v[64:67], v[0:15]
	ds_read_b128 v[222:225], v208 offset:40960
	s_min_u32 s8, s31, s16
	s_lshl_b32 s8, s8, 14
	s_add_u32 s26, s22, s8
	s_addc_u32 s27, s23, 0
	global_load_dwordx4 v[90:93], v210, s[26:27]
	s_add_i32 s9, s31, -1
	s_min_u32 s9, s9, s16
	s_lshl_b32 s9, s9, 7
	s_add_u32 s8, s24, s9
	s_addc_u32 s9, s25, 0
	global_load_dwordx4 v[94:97], v211, s[8:9]
	s_add_i32 s31, s31, 1
	v_exp_f32_e32 v54, v54
	v_exp_f32_e32 v55, v55
	v_add_f32_e32 v72, v72, v54
	v_add_f32_e32 v73, v73, v55
	v_cvt_pk_bf16_f32 v201, v54, v55
	s_waitcnt lgkmcnt(7)
	v_mfma_f32_32x32x16_bf16 v[32:47], v[234:237], v[82:85], v[32:47]
	ds_read_b128 v[226:229], v207 offset:53248
	v_exp_f32_e32 v56, v56
	v_exp_f32_e32 v57, v57
	v_add_f32_e32 v72, v72, v56
	v_add_f32_e32 v73, v73, v57
	v_cvt_pk_bf16_f32 v202, v56, v57
	s_waitcnt lgkmcnt(7)
	v_mfma_f32_32x32x16_bf16 v[16:31], v[238:241], v[68:71], v[16:31]
	ds_read_b128 v[230:233], v208 offset:45056
	v_exp_f32_e32 v58, v58
	v_exp_f32_e32 v59, v59
	v_add_f32_e32 v72, v72, v58
	v_add_f32_e32 v73, v73, v59
	v_cvt_pk_bf16_f32 v203, v58, v59
	s_waitcnt lgkmcnt(7)
	v_mfma_f32_32x32x16_bf16 v[32:47], v[242:245], v[86:89], v[32:47]
	ds_read_b128 v[234:237], v208 offset:53248
	v_exp_f32_e32 v60, v60
	v_exp_f32_e32 v61, v61
	v_add_f32_e32 v72, v72, v60
	v_add_f32_e32 v73, v73, v61
	v_cvt_pk_bf16_f32 v204, v60, v61
	s_waitcnt lgkmcnt(7)
	v_mfma_f32_32x32x16_bf16 v[0:15], v[246:249], v[68:71], v[0:15]
	ds_read_b128 v[238:241], v209 offset:40960
	v_exp_f32_e32 v62, v62
	v_exp_f32_e32 v63, v63
	v_add_f32_e32 v72, v72, v62
	v_add_f32_e32 v73, v73, v63
	v_cvt_pk_bf16_f32 v205, v62, v63
	s_waitcnt lgkmcnt(5)
	v_mfma_f32_32x32x16_bf16 v[48:63], v[218:221], v[74:77], 0
	ds_read_b128 v[242:245], v209 offset:53248
	v_exp_f32_e32 v32, v32
	v_exp_f32_e32 v33, v33
	v_add_f32_e32 v72, v72, v32
	v_add_f32_e32 v73, v73, v33
	v_cvt_pk_bf16_f32 v64, v32, v33
	s_waitcnt lgkmcnt(5)
	v_mfma_f32_32x32x16_bf16 v[16:31], v[222:225], v[198:201], v[16:31]
	ds_read_b128 v[246:249], v209 offset:45056
	v_exp_f32_e32 v34, v34
	v_exp_f32_e32 v35, v35
	v_add_f32_e32 v72, v72, v34
	v_add_f32_e32 v73, v73, v35
	v_cvt_pk_bf16_f32 v65, v34, v35
	s_waitcnt lgkmcnt(5)
	v_mfma_f32_32x32x16_bf16 v[48:63], v[226:229], v[78:81], v[48:63]
	ds_read_b128 v[218:221], v206
	v_exp_f32_e32 v36, v36
	v_exp_f32_e32 v37, v37
	v_add_f32_e32 v72, v72, v36
	v_add_f32_e32 v73, v73, v37
	v_cvt_pk_bf16_f32 v66, v36, v37
	s_waitcnt lgkmcnt(5)
	v_mfma_f32_32x32x16_bf16 v[0:15], v[230:233], v[198:201], v[0:15]
	ds_read_b128 v[222:225], v206 offset:57344
	v_exp_f32_e32 v38, v38
	v_exp_f32_e32 v39, v39
	v_add_f32_e32 v72, v72, v38
	v_add_f32_e32 v73, v73, v39
	v_cvt_pk_bf16_f32 v67, v38, v39
	s_waitcnt lgkmcnt(5)
	v_mfma_f32_32x32x16_bf16 v[48:63], v[234:237], v[82:85], v[48:63]
	ds_read_b128 v[226:229], v207
	v_exp_f32_e32 v40, v40
	v_exp_f32_e32 v41, v41
	v_add_f32_e32 v72, v72, v40
	v_add_f32_e32 v73, v73, v41
	v_cvt_pk_bf16_f32 v68, v40, v41
	s_waitcnt lgkmcnt(5)
	v_mfma_f32_32x32x16_bf16 v[16:31], v[238:241], v[202:205], v[16:31]
	ds_read_b128 v[230:233], v206 offset:61440
	v_exp_f32_e32 v42, v42
	v_exp_f32_e32 v43, v43
	v_add_f32_e32 v72, v72, v42
	v_add_f32_e32 v73, v73, v43
	v_cvt_pk_bf16_f32 v69, v42, v43
	s_waitcnt lgkmcnt(5)
	v_mfma_f32_32x32x16_bf16 v[48:63], v[242:245], v[86:89], v[48:63]
	ds_read_b128 v[234:237], v208
	v_exp_f32_e32 v44, v44
	v_exp_f32_e32 v45, v45
	v_add_f32_e32 v72, v72, v44
	v_add_f32_e32 v73, v73, v45
	v_cvt_pk_bf16_f32 v70, v44, v45
	s_waitcnt lgkmcnt(5)
	v_mfma_f32_32x32x16_bf16 v[0:15], v[246:249], v[202:205], v[0:15]
	ds_read_b128 v[238:241], v207 offset:57344
	v_exp_f32_e32 v46, v46
	v_exp_f32_e32 v47, v47
	v_add_f32_e32 v72, v72, v46
	v_add_f32_e32 v73, v73, v47
	v_cvt_pk_bf16_f32 v71, v46, v47
	s_barrier
	s_add_i32 s33, s33, -1
	s_cmp_eq_u32 s33, 0
	s_cbranch_scc1 .Lattn_tail
	s_waitcnt lgkmcnt(5)
	v_mfma_f32_32x32x16_bf16 v[32:47], v[218:221], v[74:77], 0
	ds_read_b128 v[242:245], v209
	v_exp_f32_e32 v48, v48
	v_exp_f32_e32 v49, v49
	v_add_f32_e32 v72, v72, v48
	v_add_f32_e32 v73, v73, v49
	v_cvt_pk_bf16_f32 v198, v48, v49
	s_waitcnt lgkmcnt(5)
	v_mfma_f32_32x32x16_bf16 v[16:31], v[222:225], v[64:67], v[16:31]
	ds_read_b128 v[246:249], v207 offset:61440
	s_waitcnt vmcnt(3)
	ds_write_b128 v150, v[250:253] offset:32768
	s_waitcnt vmcnt(2)
	ds_write_b128 v150, v[138:141] offset:24576
	v_exp_f32_e32 v50, v50
	v_exp_f32_e32 v51, v51
	v_add_f32_e32 v72, v72, v50
	v_add_f32_e32 v73, v73, v51
	v_cvt_pk_bf16_f32 v199, v50, v51
	s_waitcnt lgkmcnt(7)
	v_mfma_f32_32x32x16_bf16 v[32:47], v[226:229], v[78:81], v[32:47]
	ds_read_b128 v[218:221], v206 offset:4096
	v_exp_f32_e32 v52, v52
	v_exp_f32_e32 v53, v53
	v_add_f32_e32 v72, v72, v52
	v_add_f32_e32 v73, v73, v53
	v_cvt_pk_bf16_f32 v200, v52, v53
	s_waitcnt lgkmcnt(7)
	v_mfma_f32_32x32x16_bf16 v[0:15], v[230:233], v[64:67], v[0:15]
	ds_read_b128 v[222:225], v208 offset:57344
	s_min_u32 s8, s31, s16
	s_lshl_b32 s8, s8, 14
	s_add_u32 s26, s22, s8
	s_addc_u32 s27, s23, 0
	global_load_dwordx4 v[250:253], v210, s[26:27]
	s_add_i32 s9, s31, -1
	s_min_u32 s9, s9, s16
	s_lshl_b32 s9, s9, 7
	s_add_u32 s8, s24, s9
	s_addc_u32 s9, s25, 0
	global_load_dwordx4 v[138:141], v211, s[8:9]
	s_add_i32 s31, s31, 1
	v_exp_f32_e32 v54, v54
	v_exp_f32_e32 v55, v55
	v_add_f32_e32 v72, v72, v54
	v_add_f32_e32 v73, v73, v55
	v_cvt_pk_bf16_f32 v201, v54, v55
	s_waitcnt lgkmcnt(7)
	v_mfma_f32_32x32x16_bf16 v[32:47], v[234:237], v[82:85], v[32:47]
	ds_read_b128 v[226:229], v207 offset:4096
	v_exp_f32_e32 v56, v56
	v_exp_f32_e32 v57, v57
	v_add_f32_e32 v72, v72, v56
	v_add_f32_e32 v73, v73, v57
	v_cvt_pk_bf16_f32 v202, v56, v57
	s_waitcnt lgkmcnt(7)
	v_mfma_f32_32x32x16_bf16 v[16:31], v[238:241], v[68:71], v[16:31]
	ds_read_b128 v[230:233], v208 offset:61440
	v_exp_f32_e32 v58, v58
	v_exp_f32_e32 v59, v59
	v_add_f32_e32 v72, v72, v58
	v_add_f32_e32 v73, v73, v59
	v_cvt_pk_bf16_f32 v203, v58, v59
	s_waitcnt lgkmcnt(7)
	v_mfma_f32_32x32x16_bf16 v[32:47], v[242:245], v[86:89], v[32:47]
	ds_read_b128 v[234:237], v208 offset:4096
	v_exp_f32_e32 v60, v60
	v_exp_f32_e32 v61, v61
	v_add_f32_e32 v72, v72, v60
	v_add_f32_e32 v73, v73, v61
	v_cvt_pk_bf16_f32 v204, v60, v61
	s_waitcnt lgkmcnt(7)
	v_mfma_f32_32x32x16_bf16 v[0:15], v[246:249], v[68:71], v[0:15]
	ds_read_b128 v[238:241], v209 offset:57344
	v_exp_f32_e32 v62, v62
	v_exp_f32_e32 v63, v63
	v_add_f32_e32 v72, v72, v62
	v_add_f32_e32 v73, v73, v63
	v_cvt_pk_bf16_f32 v205, v62, v63
	s_waitcnt lgkmcnt(5)
	v_mfma_f32_32x32x16_bf16 v[48:63], v[218:221], v[74:77], 0
	ds_read_b128 v[242:245], v209 offset:4096
	v_exp_f32_e32 v32, v32
	v_exp_f32_e32 v33, v33
	v_add_f32_e32 v72, v72, v32
	v_add_f32_e32 v73, v73, v33
	v_cvt_pk_bf16_f32 v64, v32, v33
	s_waitcnt lgkmcnt(5)
	v_mfma_f32_32x32x16_bf16 v[16:31], v[222:225], v[198:201], v[16:31]
	ds_read_b128 v[246:249], v209 offset:61440
	v_exp_f32_e32 v34, v34
	v_exp_f32_e32 v35, v35
	v_add_f32_e32 v72, v72, v34
	v_add_f32_e32 v73, v73, v35
	v_cvt_pk_bf16_f32 v65, v34, v35
	s_waitcnt lgkmcnt(5)
	v_mfma_f32_32x32x16_bf16 v[48:63], v[226:229], v[78:81], v[48:63]
	ds_read_b128 v[218:221], v206 offset:16384
	v_exp_f32_e32 v36, v36
	v_exp_f32_e32 v37, v37
	v_add_f32_e32 v72, v72, v36
	v_add_f32_e32 v73, v73, v37
	v_cvt_pk_bf16_f32 v66, v36, v37
	s_waitcnt lgkmcnt(5)
	v_mfma_f32_32x32x16_bf16 v[0:15], v[230:233], v[198:201], v[0:15]
	ds_read_b128 v[222:225], v206 offset:8192
	v_exp_f32_e32 v38, v38
	v_exp_f32_e32 v39, v39
	v_add_f32_e32 v72, v72, v38
	v_add_f32_e32 v73, v73, v39
	v_cvt_pk_bf16_f32 v67, v38, v39
	s_waitcnt lgkmcnt(5)
	v_mfma_f32_32x32x16_bf16 v[48:63], v[234:237], v[82:85], v[48:63]
	ds_read_b128 v[226:229], v207 offset:16384
	v_exp_f32_e32 v40, v40
	v_exp_f32_e32 v41, v41
	v_add_f32_e32 v72, v72, v40
	v_add_f32_e32 v73, v73, v41
	v_cvt_pk_bf16_f32 v68, v40, v41
	s_waitcnt lgkmcnt(5)
	v_mfma_f32_32x32x16_bf16 v[16:31], v[238:241], v[202:205], v[16:31]
	ds_read_b128 v[230:233], v206 offset:12288
	v_exp_f32_e32 v42, v42
	v_exp_f32_e32 v43, v43
	v_add_f32_e32 v72, v72, v42
	v_add_f32_e32 v73, v73, v43
	v_cvt_pk_bf16_f32 v69, v42, v43
	s_waitcnt lgkmcnt(5)
	v_mfma_f32_32x32x16_bf16 v[48:63], v[242:245], v[86:89], v[48:63]
	ds_read_b128 v[234:237], v208 offset:16384
	v_exp_f32_e32 v44, v44
	v_exp_f32_e32 v45, v45
	v_add_f32_e32 v72, v72, v44
	v_add_f32_e32 v73, v73, v45
	v_cvt_pk_bf16_f32 v70, v44, v45
	s_waitcnt lgkmcnt(5)
	v_mfma_f32_32x32x16_bf16 v[0:15], v[246:249], v[202:205], v[0:15]
	ds_read_b128 v[238:241], v207 offset:8192
	v_exp_f32_e32 v46, v46
	v_exp_f32_e32 v47, v47
	v_add_f32_e32 v72, v72, v46
	v_add_f32_e32 v73, v73, v47
	v_cvt_pk_bf16_f32 v71, v46, v47
	s_barrier
	s_branch .Lattn_loop
.Lattn_tail:
	v_exp_f32_e32 v48, v48
	v_exp_f32_e32 v49, v49
	v_add_f32_e32 v72, v72, v48
	v_add_f32_e32 v73, v73, v49
	v_cvt_pk_bf16_f32 v198, v48, v49
	s_waitcnt lgkmcnt(4)
	v_mfma_f32_32x32x16_bf16 v[16:31], v[222:225], v[64:67], v[16:31]
	ds_read_b128 v[246:249], v207 offset:61440
	v_exp_f32_e32 v50, v50
	v_exp_f32_e32 v51, v51
	v_add_f32_e32 v72, v72, v50
	v_add_f32_e32 v73, v73, v51
	v_cvt_pk_bf16_f32 v199, v50, v51
	v_exp_f32_e32 v52, v52
	v_exp_f32_e32 v53, v53
	v_add_f32_e32 v72, v72, v52
	v_add_f32_e32 v73, v73, v53
	v_cvt_pk_bf16_f32 v200, v52, v53
	s_waitcnt lgkmcnt(3)
	v_mfma_f32_32x32x16_bf16 v[0:15], v[230:233], v[64:67], v[0:15]
	ds_read_b128 v[222:225], v208 offset:57344
	v_exp_f32_e32 v54, v54
	v_exp_f32_e32 v55, v55
	v_add_f32_e32 v72, v72, v54
	v_add_f32_e32 v73, v73, v55
	v_cvt_pk_bf16_f32 v201, v54, v55
	v_exp_f32_e32 v56, v56
	v_exp_f32_e32 v57, v57
	v_add_f32_e32 v72, v72, v56
	v_add_f32_e32 v73, v73, v57
	v_cvt_pk_bf16_f32 v202, v56, v57
	s_waitcnt lgkmcnt(2)
	v_mfma_f32_32x32x16_bf16 v[16:31], v[238:241], v[68:71], v[16:31]
	ds_read_b128 v[230:233], v208 offset:61440
	v_exp_f32_e32 v58, v58
	v_exp_f32_e32 v59, v59
	v_add_f32_e32 v72, v72, v58
	v_add_f32_e32 v73, v73, v59
	v_cvt_pk_bf16_f32 v203, v58, v59
	v_exp_f32_e32 v60, v60
	v_exp_f32_e32 v61, v61
	v_add_f32_e32 v72, v72, v60
	v_add_f32_e32 v73, v73, v61
	v_cvt_pk_bf16_f32 v204, v60, v61
	s_waitcnt lgkmcnt(2)
	v_mfma_f32_32x32x16_bf16 v[0:15], v[246:249], v[68:71], v[0:15]
	ds_read_b128 v[238:241], v209 offset:57344
	v_exp_f32_e32 v62, v62
	v_exp_f32_e32 v63, v63
	v_add_f32_e32 v72, v72, v62
	v_add_f32_e32 v73, v73, v63
	v_cvt_pk_bf16_f32 v205, v62, v63
	s_waitcnt lgkmcnt(2)
	v_mfma_f32_32x32x16_bf16 v[16:31], v[222:225], v[198:201], v[16:31]
	ds_read_b128 v[246:249], v209 offset:61440
	s_waitcnt lgkmcnt(2)
	v_mfma_f32_32x32x16_bf16 v[0:15], v[230:233], v[198:201], v[0:15]
	s_waitcnt lgkmcnt(1)
	v_mfma_f32_32x32x16_bf16 v[16:31], v[238:241], v[202:205], v[16:31]
	s_waitcnt lgkmcnt(0)
	v_mfma_f32_32x32x16_bf16 v[0:15], v[246:249], v[202:205], v[0:15]
	v_add_f32_e32 v72, v72, v73
	s_waitcnt vmcnt(0) lgkmcnt(0)
	s_barrier
	s_branch .LBB0_298
